# odd in-proj epilogue stores also lane-transposed through LDS (row-contiguous 64-B segments)
# speedup vs baseline: 1.0639x; 1.0000x over previous
; __device__ __forceinline__ f32x4 gelu4(f32x4 v) { f32x2 a = gelu_pk((f32x2){v[0], v[1]}), b = gelu_pk((f32x2){v[2], v[3]}); return (f32x4){a.x, a.y, b.x, b.y}; }
; __device__ __forceinline__ float sq4(f32x4 a) { return (a[0] * a[0] + a[1] * a[1]) + (a[2] * a[2] + a[3] * a[3]); }
; __device__ __forceinline__ f32x2 gelu_pk(f32x2 v) {
;     const f32x2 av = __builtin_elementwise_abs(v), d = av * 0.2316418882f + 1.0f;
;     f32x2 t; t.x = __builtin_amdgcn_rcpf(d.x); t.y = __builtin_amdgcn_rcpf(d.y);
;     f32x2 q = t * 0.5307027145f + (-0.7265760135f); q = q * t + 0.7107068705f; q = q * t + (-0.142248368f); q = q * t + 0.127414796f; q = q * t;
;     const f32x2 s = (v * v) * (-0.72134752044f);
;     f32x2 e; e.x = __builtin_amdgcn_exp2f(s.x); e.y = __builtin_amdgcn_exp2f(s.y);
;     const f32x2 m = v * (q * e), r = v - m;
;     f32x2 o; o.x = v.x < 0.f ? m.x : r.x; o.y = v.y < 0.f ? m.y : r.y; return o;
; }
;     __device__ __forceinline__ void operator()(const f32x4 (&acc)[2][2][4][2], const Unit& u, int wr, int wc, int fr_, int fq_, int slot) const {
;     ...
;             for (int m = 0; m < 4; ++m) rs[ai][m] = rst[slot * 256 + ai * HALF + wr * 64 + m * 16 + fr];
; #pragma unroll
;         for (int ai = 0; ai < 2; ++ai)
; #pragma unroll
;             for (int m = 0; m < 4; ++m) {
;                 const int row = u.pm * BM + ai * HALF + wr * 64 + m * 16 + fr;
;                 const float r = rs[ai][m];
;                 bf16_t* rowp = P + (size_t)row * ODD_IN + col0;
;                 float sq = 0.f;
; #pragma unroll
;                 for (int bj = 0; bj < 2; ++bj) {
;                     f32x4 v0 = acc[ai][bj][m][0] * r, v1 = acc[ai][bj][m][1] * r;
;                     if (pn >= 4 && pn < 8) { v0 = gelu4(v0); v1 = gelu4(v1); sq += sq4(v0) + sq4(v1); }
.LBB0_273:
	s_lshl_b32 s8, s22, 10
	s_and_b32 s8, s8, 0x400
	v_mov_b32_e32 v172, v165
	v_mov_b32_e32 v170, v166
	v_lshrrev_b32_e32 v200, 2, v165
	v_lshl_add_u32 v200, v166, 2, v200
	v_and_b32_e32 v201, 3, v165
	v_lshrrev_b32_e32 v202, 6, v233
	v_lshlrev_b32_e32 v202, 11, v202
	v_add_u32_e32 v202, 0x20000, v202
	v_mul_u32_u24_e32 v203, 0x50, v165
	v_lshl_add_u32 v203, v166, 4, v203
	v_add_u32_e32 v203, v203, v202
	v_mul_u32_u24_e32 v204, 0x50, v200
	v_lshl_add_u32 v204, v201, 4, v204
	v_add_u32_e32 v204, v204, v202
	s_add_i32 s8, s30, s8
	v_mov_b32_e32 v171, 0
	v_lshl_add_u32 v150, v172, 2, s8
	ds_read2_b32 v[156:157], v150 offset1:16
	ds_read2_b32 v[154:155], v150 offset0:32 offset1:48
	ds_read2_b32 v[152:153], v150 offset0:128 offset1:144
	ds_read2_b32 v[150:151], v150 offset0:160 offset1:176
	s_and_b32 s8, s92, -4
	s_cmp_eq_u32 s8, 4
	s_cselect_b64 s[94:95], -1, 0
	s_cmp_lg_u32 s8, 4
	s_waitcnt lgkmcnt(0)
	v_pk_mul_f32 v[160:161], v[136:137], v[156:157] op_sel_hi:[1,0]
	v_pk_mul_f32 v[162:163], v[134:135], v[156:157] op_sel_hi:[1,0]
	v_pk_mul_f32 v[136:137], v[132:133], v[156:157] op_sel_hi:[1,0]
	v_pk_mul_f32 v[158:159], v[130:131], v[156:157] op_sel_hi:[1,0]
	s_cbranch_scc1 .LBB0_275
	v_and_b32_e32 v177, 0x7fffffff, v161
	v_and_b32_e32 v176, 0x7fffffff, v160
	v_pk_fma_f32 v[176:177], v[176:177], s[14:15], 1.0 op_sel_hi:[1,0,0]
	s_mov_b32 s8, 0xbf3a00e3
	v_rcp_f32_e32 v176, v176
	v_rcp_f32_e32 v177, v177
	v_mov_b64_e32 v[132:133], s[8:9]
	v_and_b32_e32 v131, 0x7fffffff, v163
	v_and_b32_e32 v130, 0x7fffffff, v162
	v_pk_fma_f32 v[178:179], v[176:177], s[34:35], v[132:133] op_sel_hi:[1,0,0]
	v_pk_fma_f32 v[130:131], v[130:131], s[14:15], 1.0 op_sel_hi:[1,0,0]
	v_pk_fma_f32 v[178:179], v[176:177], v[178:179], s[56:57] op_sel_hi:[1,1,0]
	v_rcp_f32_e32 v130, v130
	v_pk_fma_f32 v[178:179], v[176:177], v[178:179], s[10:11] op_sel_hi:[1,1,0]
	v_rcp_f32_e32 v131, v131
	v_pk_fma_f32 v[178:179], v[176:177], v[178:179], s[18:19] op_sel_hi:[1,1,0]
	v_and_b32_e32 v185, 0x7fffffff, v137
	v_pk_mul_f32 v[176:177], v[176:177], v[178:179]
	v_and_b32_e32 v179, 0x7fffffff, v159
	v_and_b32_e32 v178, 0x7fffffff, v158
	v_pk_fma_f32 v[178:179], v[178:179], s[14:15], 1.0 op_sel_hi:[1,0,0]
	v_and_b32_e32 v184, 0x7fffffff, v136
	v_rcp_f32_e32 v178, v178
	v_rcp_f32_e32 v179, v179
	v_pk_fma_f32 v[184:185], v[184:185], s[14:15], 1.0 op_sel_hi:[1,0,0]
	v_pk_mul_f32 v[182:183], v[158:159], v[158:159]
	v_rcp_f32_e32 v184, v184
	v_pk_fma_f32 v[180:181], v[178:179], s[34:35], v[132:133] op_sel_hi:[1,0,0]
	v_rcp_f32_e32 v185, v185
	v_pk_fma_f32 v[134:135], v[130:131], s[34:35], v[132:133] op_sel_hi:[1,0,0]
	v_pk_mul_f32 v[174:175], v[162:163], v[162:163]
	v_pk_fma_f32 v[180:181], v[178:179], v[180:181], s[56:57] op_sel_hi:[1,1,0]
	v_pk_mul_f32 v[182:183], v[182:183], s[12:13] op_sel_hi:[1,0]
	v_pk_fma_f32 v[134:135], v[130:131], v[134:135], s[56:57] op_sel_hi:[1,1,0]
	v_pk_mul_f32 v[174:175], v[174:175], s[12:13] op_sel_hi:[1,0]
	v_pk_fma_f32 v[180:181], v[178:179], v[180:181], s[10:11] op_sel_hi:[1,1,0]
	v_exp_f32_e32 v182, v182
	v_exp_f32_e32 v183, v183
	v_pk_fma_f32 v[134:135], v[130:131], v[134:135], s[10:11] op_sel_hi:[1,1,0]
	v_exp_f32_e32 v174, v174
	v_exp_f32_e32 v175, v175
	v_pk_fma_f32 v[180:181], v[178:179], v[180:181], s[18:19] op_sel_hi:[1,1,0]
	v_pk_fma_f32 v[134:135], v[130:131], v[134:135], s[18:19] op_sel_hi:[1,1,0]
	v_pk_mul_f32 v[178:179], v[178:179], v[180:181]
	v_pk_mul_f32 v[180:181], v[136:137], v[136:137]
	v_pk_fma_f32 v[132:133], v[184:185], s[34:35], v[132:133] op_sel_hi:[1,0,0]
	v_pk_mul_f32 v[130:131], v[130:131], v[134:135]
	v_pk_mul_f32 v[134:135], v[160:161], v[160:161]
	v_pk_fma_f32 v[132:133], v[184:185], v[132:133], s[56:57] op_sel_hi:[1,1,0]
	v_pk_mul_f32 v[180:181], v[180:181], s[12:13] op_sel_hi:[1,0]
	v_pk_mul_f32 v[134:135], v[134:135], s[12:13] op_sel_hi:[1,0]
	v_pk_mul_f32 v[178:179], v[182:183], v[178:179]
	v_exp_f32_e32 v180, v180
	v_exp_f32_e32 v181, v181
	v_pk_fma_f32 v[132:133], v[184:185], v[132:133], s[10:11] op_sel_hi:[1,1,0]
	v_pk_mul_f32 v[130:131], v[174:175], v[130:131]
	v_exp_f32_e32 v134, v134
	v_exp_f32_e32 v135, v135
	v_pk_mul_f32 v[182:183], v[158:159], v[178:179]
	v_pk_fma_f32 v[178:179], v[158:159], v[178:179], v[158:159] neg_lo:[1,0,0] neg_hi:[1,0,0]
	v_pk_fma_f32 v[132:133], v[184:185], v[132:133], s[18:19] op_sel_hi:[1,1,0]
	v_cmp_gt_f32_e32 vcc, 0, v158
	v_pk_mul_f32 v[174:175], v[162:163], v[130:131]
	v_pk_fma_f32 v[130:131], v[162:163], v[130:131], v[162:163] neg_lo:[1,0,0] neg_hi:[1,0,0]
	v_pk_mul_f32 v[132:133], v[184:185], v[132:133]
	v_cndmask_b32_e32 v185, v178, v182, vcc
	v_cmp_gt_f32_e32 vcc, 0, v162
	v_pk_mul_f32 v[132:133], v[180:181], v[132:133]
	v_pk_mul_f32 v[134:135], v[134:135], v[176:177]
	v_cndmask_b32_e32 v184, v130, v174, vcc
	v_cmp_gt_f32_e32 vcc, 0, v159
	v_pk_mul_f32 v[180:181], v[136:137], v[132:133]
	v_pk_fma_f32 v[132:133], v[136:137], v[132:133], v[136:137] neg_lo:[1,0,0] neg_hi:[1,0,0]
	v_cndmask_b32_e32 v159, v179, v183, vcc
	v_cmp_gt_f32_e32 vcc, 0, v163
	v_pk_mul_f32 v[176:177], v[160:161], v[134:135]
	v_pk_fma_f32 v[134:135], v[160:161], v[134:135], v[160:161] neg_lo:[1,0,0] neg_hi:[1,0,0]
	v_cndmask_b32_e32 v158, v131, v175, vcc
	v_cmp_gt_f32_e32 vcc, 0, v136
	v_mov_b32_e32 v162, v184
	v_mov_b32_e32 v163, v158
	v_cndmask_b32_e32 v131, v132, v180, vcc
	v_cmp_gt_f32_e32 vcc, 0, v160
	s_nop 1
	v_cndmask_b32_e32 v130, v134, v176, vcc
	v_cmp_gt_f32_e32 vcc, 0, v137
	v_mov_b32_e32 v160, v130
	s_nop 0
	v_cndmask_b32_e32 v137, v133, v181, vcc
	v_cmp_gt_f32_e32 vcc, 0, v161
	v_pk_mul_f32 v[132:133], v[158:159], v[158:159]
	v_mov_b32_e32 v158, v185
	v_cndmask_b32_e32 v136, v135, v177, vcc
	v_pk_mul_f32 v[134:135], v[136:137], v[136:137]
	v_pk_fma_f32 v[132:133], v[184:185], v[184:185], v[132:133]
	v_pk_fma_f32 v[134:135], v[130:131], v[130:131], v[134:135]
	v_mov_b32_e32 v161, v136
	v_pk_add_f32 v[132:133], v[132:133], v[134:135]
	v_mov_b32_e32 v136, v131
	v_add_f32_e32 v171, v132, v133
; __device__ __forceinline__ f32x4 gelu4(f32x4 v) { f32x2 a = gelu_pk((f32x2){v[0], v[1]}), b = gelu_pk((f32x2){v[2], v[3]}); return (f32x4){a.x, a.y, b.x, b.y}; }
; __device__ __forceinline__ u32x4 pack8(f32x4 a, f32x4 b) { u32x4 w; w.x = cvt_pk_bf16(a[0], a[1]); w.y = cvt_pk_bf16(a[2], a[3]); w.z = cvt_pk_bf16(b[0], b[1]); w.w = cvt_pk_bf16(b[2], b[3]); return w; }
; __device__ __forceinline__ float sq4(f32x4 a) { return (a[0] * a[0] + a[1] * a[1]) + (a[2] * a[2] + a[3] * a[3]); }
; __device__ __forceinline__ f32x2 gelu_pk(f32x2 v) {
;     const f32x2 av = __builtin_elementwise_abs(v), d = av * 0.2316418882f + 1.0f;
;     f32x2 t; t.x = __builtin_amdgcn_rcpf(d.x); t.y = __builtin_amdgcn_rcpf(d.y);
;     f32x2 q = t * 0.5307027145f + (-0.7265760135f); q = q * t + 0.7107068705f; q = q * t + (-0.142248368f); q = q * t + 0.127414796f; q = q * t;
;     const f32x2 s = (v * v) * (-0.72134752044f);
;     f32x2 e; e.x = __builtin_amdgcn_exp2f(s.x); e.y = __builtin_amdgcn_exp2f(s.y);
;     const f32x2 m = v * (q * e), r = v - m;
;     f32x2 o; o.x = v.x < 0.f ? m.x : r.x; o.y = v.y < 0.f ? m.y : r.y; return o;
; }
;     __device__ __forceinline__ void operator()(const f32x4 (&acc)[2][2][4][2], const Unit& u, int wr, int wc, int fr_, int fq_, int slot) const {
;     ...
;             for (int m = 0; m < 4; ++m) {
;                 const int row = u.pm * BM + ai * HALF + wr * 64 + m * 16 + fr;
;                 const float r = rs[ai][m];
;                 bf16_t* rowp = P + (size_t)row * ODD_IN + col0;
;                 float sq = 0.f;
; #pragma unroll
;                 for (int bj = 0; bj < 2; ++bj) {
;                     f32x4 v0 = acc[ai][bj][m][0] * r, v1 = acc[ai][bj][m][1] * r;
;                     if (pn >= 4 && pn < 8) { v0 = gelu4(v0); v1 = gelu4(v1); sq += sq4(v0) + sq4(v1); }
;                     *(u32x4*)(rowp + bj * HALF) = pack8(v0, v1);
;                 }
;                 if (pn >= 4 && pn < 8) { sq = fq_sum(sq); if (fq == 0) ssv[(size_t)row * 16 + (pn - 4) * 4 + wc] = sq; }
.LBB0_275:
	s_lshl_b32 s8, s92, 8
	s_or_b32 s8, s8, s35
	v_lshl_add_u32 v130, v201, 3, s8
	s_lshl_b32 s8, s44, 8
	s_add_i32 s8, s8, s17
	v_add_u32_e32 v132, s8, v172
	v_add_u32_e32 v205, s8, v200
	v_mov_b64_e32 v[134:135], s[0:1]
	v_mov_b32_e32 v176, v156
	v_mov_b32_e32 v177, v156
	v_ashrrev_i32_e32 v131, 31, v130
	v_mad_i64_i32 v[134:135], s[8:9], v205, s33, v[134:135]
	v_cvt_pk_bf16_f32 v172, v162, v163
	v_cvt_pk_bf16_f32 v173, v160, v161
	v_cvt_pk_bf16_f32 v174, v158, v159
	v_cvt_pk_bf16_f32 v175, v136, v137
	v_mov_b32_e32 v136, v156
	v_mov_b32_e32 v137, v156
	v_cndmask_b32_e64 v133, 0, 1, s[94:95]
	v_lshl_add_u64 v[134:135], v[130:131], 1, v[134:135]
	v_pk_mul_f32 v[128:129], v[128:129], v[136:137]
	v_pk_mul_f32 v[126:127], v[126:127], v[176:177]
	v_pk_mul_f32 v[124:125], v[124:125], v[136:137]
	v_cmp_ne_u32_e64 s[42:43], 1, v133
	s_andn2_b64 vcc, exec, s[94:95]
	v_pk_mul_f32 v[122:123], v[122:123], v[176:177]
	ds_write_b128 v203, v[172:175]
	ds_read_b128 v[172:175], v204
	s_waitcnt lgkmcnt(0)
	global_store_dwordx4 v[134:135], v[172:175], off
	s_cbranch_vccnz .LBB0_277
	s_nop 0
	v_and_b32_e32 v173, 0x7fffffff, v129
	v_and_b32_e32 v172, 0x7fffffff, v128
	v_pk_fma_f32 v[172:173], v[172:173], s[14:15], 1.0 op_sel_hi:[1,0,0]
	s_mov_b32 s8, 0xbf3a00e3
	v_rcp_f32_e32 v172, v172
	v_rcp_f32_e32 v173, v173
	v_mov_b64_e32 v[158:159], s[8:9]
	v_and_b32_e32 v137, 0x7fffffff, v127
	v_and_b32_e32 v136, 0x7fffffff, v126
	v_pk_fma_f32 v[174:175], v[172:173], s[34:35], v[158:159] op_sel_hi:[1,0,0]
	v_pk_fma_f32 v[136:137], v[136:137], s[14:15], 1.0 op_sel_hi:[1,0,0]
	v_pk_fma_f32 v[174:175], v[172:173], v[174:175], s[56:57] op_sel_hi:[1,1,0]
	v_rcp_f32_e32 v136, v136
	v_pk_fma_f32 v[174:175], v[172:173], v[174:175], s[10:11] op_sel_hi:[1,1,0]
	v_rcp_f32_e32 v137, v137
	v_pk_fma_f32 v[174:175], v[172:173], v[174:175], s[18:19] op_sel_hi:[1,1,0]
	v_and_b32_e32 v181, 0x7fffffff, v125
	v_pk_mul_f32 v[172:173], v[172:173], v[174:175]
	v_and_b32_e32 v175, 0x7fffffff, v123
	v_and_b32_e32 v174, 0x7fffffff, v122
	v_pk_fma_f32 v[174:175], v[174:175], s[14:15], 1.0 op_sel_hi:[1,0,0]
	v_and_b32_e32 v180, 0x7fffffff, v124
	v_rcp_f32_e32 v174, v174
	v_rcp_f32_e32 v175, v175
	v_pk_fma_f32 v[180:181], v[180:181], s[14:15], 1.0 op_sel_hi:[1,0,0]
	v_pk_mul_f32 v[178:179], v[122:123], v[122:123]
	v_rcp_f32_e32 v180, v180
	v_pk_fma_f32 v[176:177], v[174:175], s[34:35], v[158:159] op_sel_hi:[1,0,0]
	v_rcp_f32_e32 v181, v181
	v_pk_fma_f32 v[160:161], v[136:137], s[34:35], v[158:159] op_sel_hi:[1,0,0]
	v_pk_mul_f32 v[162:163], v[126:127], v[126:127]
	v_pk_fma_f32 v[176:177], v[174:175], v[176:177], s[56:57] op_sel_hi:[1,1,0]
	v_pk_mul_f32 v[178:179], v[178:179], s[12:13] op_sel_hi:[1,0]
	v_pk_fma_f32 v[160:161], v[136:137], v[160:161], s[56:57] op_sel_hi:[1,1,0]
	v_pk_mul_f32 v[162:163], v[162:163], s[12:13] op_sel_hi:[1,0]
	v_pk_fma_f32 v[176:177], v[174:175], v[176:177], s[10:11] op_sel_hi:[1,1,0]
	v_exp_f32_e32 v178, v178
	v_exp_f32_e32 v179, v179
	v_pk_fma_f32 v[160:161], v[136:137], v[160:161], s[10:11] op_sel_hi:[1,1,0]
	v_exp_f32_e32 v162, v162
	v_exp_f32_e32 v163, v163
	v_pk_fma_f32 v[176:177], v[174:175], v[176:177], s[18:19] op_sel_hi:[1,1,0]
	v_pk_fma_f32 v[160:161], v[136:137], v[160:161], s[18:19] op_sel_hi:[1,1,0]
	v_pk_mul_f32 v[174:175], v[174:175], v[176:177]
	v_pk_mul_f32 v[176:177], v[124:125], v[124:125]
	v_pk_fma_f32 v[158:159], v[180:181], s[34:35], v[158:159] op_sel_hi:[1,0,0]
	v_pk_mul_f32 v[136:137], v[136:137], v[160:161]
	v_pk_mul_f32 v[160:161], v[128:129], v[128:129]
	v_pk_fma_f32 v[158:159], v[180:181], v[158:159], s[56:57] op_sel_hi:[1,1,0]
	v_pk_mul_f32 v[176:177], v[176:177], s[12:13] op_sel_hi:[1,0]
	v_pk_mul_f32 v[160:161], v[160:161], s[12:13] op_sel_hi:[1,0]
	v_pk_mul_f32 v[174:175], v[178:179], v[174:175]
	v_exp_f32_e32 v176, v176
	v_exp_f32_e32 v177, v177
	v_pk_fma_f32 v[158:159], v[180:181], v[158:159], s[10:11] op_sel_hi:[1,1,0]
	v_pk_mul_f32 v[136:137], v[162:163], v[136:137]
	v_exp_f32_e32 v160, v160
	v_exp_f32_e32 v161, v161
	v_pk_mul_f32 v[178:179], v[122:123], v[174:175]
	v_pk_fma_f32 v[174:175], v[122:123], v[174:175], v[122:123] neg_lo:[1,0,0] neg_hi:[1,0,0]
	v_pk_fma_f32 v[158:159], v[180:181], v[158:159], s[18:19] op_sel_hi:[1,1,0]
	v_cmp_gt_f32_e32 vcc, 0, v122
	v_pk_mul_f32 v[162:163], v[126:127], v[136:137]
	v_pk_fma_f32 v[136:137], v[126:127], v[136:137], v[126:127] neg_lo:[1,0,0] neg_hi:[1,0,0]
	v_pk_mul_f32 v[158:159], v[180:181], v[158:159]
	v_cndmask_b32_e32 v181, v174, v178, vcc
	v_cmp_gt_f32_e32 vcc, 0, v126
	v_pk_mul_f32 v[158:159], v[176:177], v[158:159]
	v_pk_mul_f32 v[160:161], v[160:161], v[172:173]
	v_cndmask_b32_e32 v180, v136, v162, vcc
	v_cmp_gt_f32_e32 vcc, 0, v123
	v_pk_mul_f32 v[176:177], v[124:125], v[158:159]
	v_pk_fma_f32 v[158:159], v[124:125], v[158:159], v[124:125] neg_lo:[1,0,0] neg_hi:[1,0,0]
	v_cndmask_b32_e32 v123, v175, v179, vcc
	v_cmp_gt_f32_e32 vcc, 0, v127
	v_pk_mul_f32 v[172:173], v[128:129], v[160:161]
	v_pk_fma_f32 v[160:161], v[128:129], v[160:161], v[128:129] neg_lo:[1,0,0] neg_hi:[1,0,0]
	v_cndmask_b32_e32 v122, v137, v163, vcc
	v_cmp_gt_f32_e32 vcc, 0, v124
	v_pk_mul_f32 v[126:127], v[122:123], v[122:123]
	s_nop 0
	v_cndmask_b32_e32 v137, v158, v176, vcc
	v_cmp_gt_f32_e32 vcc, 0, v128
	v_pk_fma_f32 v[126:127], v[180:181], v[180:181], v[126:127]
	s_nop 0
	v_cndmask_b32_e32 v136, v160, v172, vcc
	v_cmp_gt_f32_e32 vcc, 0, v125
	s_nop 1
	v_cndmask_b32_e32 v125, v159, v177, vcc
	v_cmp_gt_f32_e32 vcc, 0, v129
	s_nop 1
	v_cndmask_b32_e32 v124, v161, v173, vcc
	v_pk_mul_f32 v[128:129], v[124:125], v[124:125]
	s_nop 0
	v_pk_fma_f32 v[128:129], v[136:137], v[136:137], v[128:129]
	s_nop 0
	v_pk_add_f32 v[126:127], v[126:127], v[128:129]
	v_mov_b32_e32 v128, v136
	v_add_f32_e32 v126, v126, v127
	v_add_f32_e32 v171, v126, v171
	v_mov_b32_e32 v126, v180
	v_mov_b32_e32 v127, v122
	v_mov_b32_e32 v129, v124
	v_mov_b32_e32 v122, v181
	v_mov_b32_e32 v124, v137
.LBB0_277:
	v_ashrrev_i32_e32 v133, 31, v132
	v_cmp_eq_u32_e64 s[44:45], 0, v170
	s_lshl_b32 s46, s92, 2
	s_and_b64 vcc, exec, s[42:43]
	v_cvt_pk_bf16_f32 v126, v126, v127
	v_cvt_pk_bf16_f32 v127, v128, v129
	v_cvt_pk_bf16_f32 v128, v122, v123
	v_cvt_pk_bf16_f32 v129, v124, v125
	ds_write_b128 v203, v[126:129]
	ds_read_b128 v[126:129], v204
	s_waitcnt lgkmcnt(0)
	global_store_dwordx4 v[134:135], v[126:129], off offset:256
	s_cbranch_vccnz .LBB0_281
	v_mov_b32_e32 v122, v171
	s_nop 1
	v_permlane16_swap_b32_e32 v171, v122
	v_add_f32_e32 v122, v171, v122
	v_mov_b32_e32 v123, v122
	s_nop 1
	v_permlane32_swap_b32_e32 v122, v123
	s_and_saveexec_b64 s[92:93], s[44:45]
	s_cbranch_execz .LBB0_280
	v_readlane_b32 s8, v253, 6
	v_add_f32_e32 v124, v122, v123
	v_lshlrev_b64 v[122:123], 6, v[132:133]
	v_readlane_b32 s9, v253, 7
	s_nop 1
	v_lshl_add_u64 v[122:123], s[8:9], 0, v[122:123]
	v_lshl_add_u64 v[122:123], s[46:47], 2, v[122:123]
	s_lshl_b32 s8, s16, 2
	s_mov_b32 s9, s47
	v_lshl_add_u64 v[122:123], v[122:123], 0, s[8:9]
	global_store_dword v[122:123], v124, off offset:-64

; __device__ __forceinline__ f32x4 gelu4(f32x4 v) { f32x2 a = gelu_pk((f32x2){v[0], v[1]}), b = gelu_pk((f32x2){v[2], v[3]}); return (f32x4){a.x, a.y, b.x, b.y}; }
; __device__ __forceinline__ u32x4 pack8(f32x4 a, f32x4 b) { u32x4 w; w.x = cvt_pk_bf16(a[0], a[1]); w.y = cvt_pk_bf16(a[2], a[3]); w.z = cvt_pk_bf16(b[0], b[1]); w.w = cvt_pk_bf16(b[2], b[3]); return w; }
; __device__ __forceinline__ float sq4(f32x4 a) { return (a[0] * a[0] + a[1] * a[1]) + (a[2] * a[2] + a[3] * a[3]); }
; __device__ __forceinline__ f32x2 gelu_pk(f32x2 v) {
;     const f32x2 av = __builtin_elementwise_abs(v), d = av * 0.2316418882f + 1.0f;
;     f32x2 t; t.x = __builtin_amdgcn_rcpf(d.x); t.y = __builtin_amdgcn_rcpf(d.y);
;     f32x2 q = t * 0.5307027145f + (-0.7265760135f); q = q * t + 0.7107068705f; q = q * t + (-0.142248368f); q = q * t + 0.127414796f; q = q * t;
;     const f32x2 s = (v * v) * (-0.72134752044f);
;     f32x2 e; e.x = __builtin_amdgcn_exp2f(s.x); e.y = __builtin_amdgcn_exp2f(s.y);
;     const f32x2 m = v * (q * e), r = v - m;
;     f32x2 o; o.x = v.x < 0.f ? m.x : r.x; o.y = v.y < 0.f ? m.y : r.y; return o;
; }
;     __device__ __forceinline__ void operator()(const f32x4 (&acc)[2][2][4][2], const Unit& u, int wr, int wc, int fr_, int fq_, int slot) const {
;     ...
;             for (int m = 0; m < 4; ++m) {
;                 const int row = u.pm * BM + ai * HALF + wr * 64 + m * 16 + fr;
;                 const float r = rs[ai][m];
;                 bf16_t* rowp = P + (size_t)row * ODD_IN + col0;
;                 float sq = 0.f;
; #pragma unroll
;                 for (int bj = 0; bj < 2; ++bj) {
;                     f32x4 v0 = acc[ai][bj][m][0] * r, v1 = acc[ai][bj][m][1] * r;
;                     if (pn >= 4 && pn < 8) { v0 = gelu4(v0); v1 = gelu4(v1); sq += sq4(v0) + sq4(v1); }
;                     *(u32x4*)(rowp + bj * HALF) = pack8(v0, v1);
;                 }
;                 if (pn >= 4 && pn < 8) { sq = fq_sum(sq); if (fq == 0) ssv[(size_t)row * 16 + (pn - 4) * 4 + wc] = sq; }
.LBB0_283:
	v_add_u32_e32 v114, 16, v132
	v_mov_b64_e32 v[116:117], s[0:1]
	v_mov_b32_e32 v156, v157
	v_add_u32_e32 v206, 16, v205
	v_mad_i64_i32 v[116:117], s[8:9], v206, s33, v[116:117]
	v_cvt_pk_bf16_f32 v124, v124, v125
	v_cvt_pk_bf16_f32 v125, v122, v123
	v_cvt_pk_bf16_f32 v126, v120, v121
	v_cvt_pk_bf16_f32 v127, v118, v119
	v_mov_b32_e32 v118, v157
	v_mov_b32_e32 v119, v157
	v_lshl_add_u64 v[116:117], v[130:131], 1, v[116:117]
	v_pk_mul_f32 v[110:111], v[110:111], v[118:119]
	v_pk_mul_f32 v[108:109], v[108:109], v[156:157]
	v_pk_mul_f32 v[106:107], v[106:107], v[118:119]
	s_and_b64 vcc, exec, s[42:43]
	v_pk_mul_f32 v[104:105], v[104:105], v[156:157]
	ds_write_b128 v203, v[124:127]
	ds_read_b128 v[124:127], v204
	s_waitcnt lgkmcnt(0)
	global_store_dwordx4 v[116:117], v[124:127], off
	s_cbranch_vccnz .LBB0_285
	s_nop 0
	v_and_b32_e32 v127, 0x7fffffff, v111
	v_and_b32_e32 v126, 0x7fffffff, v110
	v_pk_fma_f32 v[126:127], v[126:127], s[14:15], 1.0 op_sel_hi:[1,0,0]
	s_mov_b32 s8, 0xbf3a00e3
	v_rcp_f32_e32 v126, v126
	v_rcp_f32_e32 v127, v127
	v_mov_b64_e32 v[120:121], s[8:9]
	v_and_b32_e32 v119, 0x7fffffff, v109
	v_and_b32_e32 v118, 0x7fffffff, v108
	v_pk_fma_f32 v[128:129], v[126:127], s[34:35], v[120:121] op_sel_hi:[1,0,0]
	v_pk_fma_f32 v[118:119], v[118:119], s[14:15], 1.0 op_sel_hi:[1,0,0]
	v_pk_fma_f32 v[128:129], v[126:127], v[128:129], s[56:57] op_sel_hi:[1,1,0]
	v_rcp_f32_e32 v118, v118
	v_pk_fma_f32 v[128:129], v[126:127], v[128:129], s[10:11] op_sel_hi:[1,1,0]
	v_rcp_f32_e32 v119, v119
	v_pk_fma_f32 v[128:129], v[126:127], v[128:129], s[18:19] op_sel_hi:[1,1,0]
	v_and_b32_e32 v157, 0x7fffffff, v107
	v_pk_mul_f32 v[126:127], v[126:127], v[128:129]
	v_and_b32_e32 v129, 0x7fffffff, v105
	v_and_b32_e32 v128, 0x7fffffff, v104
	v_pk_fma_f32 v[128:129], v[128:129], s[14:15], 1.0 op_sel_hi:[1,0,0]
	v_and_b32_e32 v156, 0x7fffffff, v106
	v_rcp_f32_e32 v128, v128
	v_rcp_f32_e32 v129, v129
	v_pk_fma_f32 v[156:157], v[156:157], s[14:15], 1.0 op_sel_hi:[1,0,0]
	v_pk_mul_f32 v[136:137], v[104:105], v[104:105]
	v_rcp_f32_e32 v156, v156
	v_pk_fma_f32 v[134:135], v[128:129], s[34:35], v[120:121] op_sel_hi:[1,0,0]
	v_rcp_f32_e32 v157, v157
	v_pk_fma_f32 v[122:123], v[118:119], s[34:35], v[120:121] op_sel_hi:[1,0,0]
	v_pk_mul_f32 v[124:125], v[108:109], v[108:109]
	v_pk_fma_f32 v[134:135], v[128:129], v[134:135], s[56:57] op_sel_hi:[1,1,0]
	v_pk_mul_f32 v[136:137], v[136:137], s[12:13] op_sel_hi:[1,0]
	v_pk_fma_f32 v[122:123], v[118:119], v[122:123], s[56:57] op_sel_hi:[1,1,0]
	v_pk_mul_f32 v[124:125], v[124:125], s[12:13] op_sel_hi:[1,0]
	v_pk_fma_f32 v[134:135], v[128:129], v[134:135], s[10:11] op_sel_hi:[1,1,0]
	v_exp_f32_e32 v136, v136
	v_exp_f32_e32 v137, v137
	v_pk_fma_f32 v[122:123], v[118:119], v[122:123], s[10:11] op_sel_hi:[1,1,0]
	v_exp_f32_e32 v124, v124
	v_exp_f32_e32 v125, v125
	v_pk_fma_f32 v[134:135], v[128:129], v[134:135], s[18:19] op_sel_hi:[1,1,0]
	v_pk_fma_f32 v[122:123], v[118:119], v[122:123], s[18:19] op_sel_hi:[1,1,0]
	v_pk_mul_f32 v[128:129], v[128:129], v[134:135]
	v_pk_mul_f32 v[134:135], v[106:107], v[106:107]
	v_pk_fma_f32 v[120:121], v[156:157], s[34:35], v[120:121] op_sel_hi:[1,0,0]
	v_pk_mul_f32 v[118:119], v[118:119], v[122:123]
	v_pk_mul_f32 v[122:123], v[110:111], v[110:111]
	v_pk_fma_f32 v[120:121], v[156:157], v[120:121], s[56:57] op_sel_hi:[1,1,0]
	v_pk_mul_f32 v[134:135], v[134:135], s[12:13] op_sel_hi:[1,0]
	v_pk_mul_f32 v[122:123], v[122:123], s[12:13] op_sel_hi:[1,0]
	v_pk_mul_f32 v[128:129], v[136:137], v[128:129]
	v_exp_f32_e32 v134, v134
	v_exp_f32_e32 v135, v135
	v_pk_fma_f32 v[120:121], v[156:157], v[120:121], s[10:11] op_sel_hi:[1,1,0]
	v_pk_mul_f32 v[118:119], v[124:125], v[118:119]
	v_exp_f32_e32 v122, v122
	v_exp_f32_e32 v123, v123
	v_pk_mul_f32 v[136:137], v[104:105], v[128:129]
	v_pk_fma_f32 v[128:129], v[104:105], v[128:129], v[104:105] neg_lo:[1,0,0] neg_hi:[1,0,0]
	v_pk_fma_f32 v[120:121], v[156:157], v[120:121], s[18:19] op_sel_hi:[1,1,0]
	v_cmp_gt_f32_e32 vcc, 0, v104
	v_pk_mul_f32 v[124:125], v[108:109], v[118:119]
	v_pk_fma_f32 v[118:119], v[108:109], v[118:119], v[108:109] neg_lo:[1,0,0] neg_hi:[1,0,0]
	v_pk_mul_f32 v[120:121], v[156:157], v[120:121]
	v_cndmask_b32_e32 v157, v128, v136, vcc
	v_cmp_gt_f32_e32 vcc, 0, v108
	v_pk_mul_f32 v[120:121], v[134:135], v[120:121]
	v_pk_mul_f32 v[122:123], v[122:123], v[126:127]
	v_cndmask_b32_e32 v156, v118, v124, vcc
	v_cmp_gt_f32_e32 vcc, 0, v105
	v_pk_mul_f32 v[134:135], v[106:107], v[120:121]
	v_pk_fma_f32 v[120:121], v[106:107], v[120:121], v[106:107] neg_lo:[1,0,0] neg_hi:[1,0,0]
	v_cndmask_b32_e32 v105, v129, v137, vcc
	v_cmp_gt_f32_e32 vcc, 0, v109
	v_pk_mul_f32 v[126:127], v[110:111], v[122:123]
	v_pk_fma_f32 v[122:123], v[110:111], v[122:123], v[110:111] neg_lo:[1,0,0] neg_hi:[1,0,0]
	v_cndmask_b32_e32 v104, v119, v125, vcc
	v_cmp_gt_f32_e32 vcc, 0, v106
	v_pk_mul_f32 v[108:109], v[104:105], v[104:105]
	s_nop 0
	v_cndmask_b32_e32 v119, v120, v134, vcc
	v_cmp_gt_f32_e32 vcc, 0, v110
	v_pk_fma_f32 v[108:109], v[156:157], v[156:157], v[108:109]
	s_nop 0
	v_cndmask_b32_e32 v118, v122, v126, vcc
	v_cmp_gt_f32_e32 vcc, 0, v107
	s_nop 1
	v_cndmask_b32_e32 v107, v121, v135, vcc
	v_cmp_gt_f32_e32 vcc, 0, v111
	s_nop 1
	v_cndmask_b32_e32 v106, v123, v127, vcc
	v_pk_mul_f32 v[110:111], v[106:107], v[106:107]
	s_nop 0
	v_pk_fma_f32 v[110:111], v[118:119], v[118:119], v[110:111]
	s_nop 0
	v_pk_add_f32 v[108:109], v[108:109], v[110:111]
	v_mov_b32_e32 v110, v118
	v_add_f32_e32 v108, v108, v109
	v_add_f32_e32 v115, v108, v115
	v_mov_b32_e32 v108, v156
	v_mov_b32_e32 v109, v104
	v_mov_b32_e32 v111, v106
	v_mov_b32_e32 v104, v157
	v_mov_b32_e32 v106, v119
.LBB0_285:
	s_and_b64 vcc, exec, s[42:43]
	v_cvt_pk_bf16_f32 v108, v108, v109
	v_cvt_pk_bf16_f32 v109, v110, v111
	v_cvt_pk_bf16_f32 v110, v104, v105
	v_cvt_pk_bf16_f32 v111, v106, v107
	ds_write_b128 v203, v[108:111]
	ds_read_b128 v[108:111], v204
	s_waitcnt lgkmcnt(0)
	global_store_dwordx4 v[116:117], v[108:111], off offset:256
	s_cbranch_vccnz .LBB0_289
	v_mov_b32_e32 v104, v115
	s_nop 1
	v_permlane16_swap_b32_e32 v115, v104
	v_add_f32_e32 v104, v115, v104
	v_mov_b32_e32 v105, v104
	s_nop 1
	v_permlane32_swap_b32_e32 v104, v105
	s_and_saveexec_b64 s[92:93], s[44:45]
	s_cbranch_execz .LBB0_288
	v_ashrrev_i32_e32 v115, 31, v114
	v_readlane_b32 s8, v253, 6
	v_add_f32_e32 v106, v104, v105
	v_lshlrev_b64 v[104:105], 6, v[114:115]
	v_readlane_b32 s9, v253, 7
	s_nop 1
	v_lshl_add_u64 v[104:105], s[8:9], 0, v[104:105]
	v_lshl_add_u64 v[104:105], s[46:47], 2, v[104:105]
	s_lshl_b32 s8, s16, 2
	s_mov_b32 s9, s47
	v_lshl_add_u64 v[104:105], v[104:105], 0, s[8:9]
	global_store_dword v[104:105], v106, off offset:-64

; __device__ __forceinline__ f32x4 gelu4(f32x4 v) { f32x2 a = gelu_pk((f32x2){v[0], v[1]}), b = gelu_pk((f32x2){v[2], v[3]}); return (f32x4){a.x, a.y, b.x, b.y}; }
; __device__ __forceinline__ u32x4 pack8(f32x4 a, f32x4 b) { u32x4 w; w.x = cvt_pk_bf16(a[0], a[1]); w.y = cvt_pk_bf16(a[2], a[3]); w.z = cvt_pk_bf16(b[0], b[1]); w.w = cvt_pk_bf16(b[2], b[3]); return w; }
; __device__ __forceinline__ float sq4(f32x4 a) { return (a[0] * a[0] + a[1] * a[1]) + (a[2] * a[2] + a[3] * a[3]); }
; __device__ __forceinline__ f32x2 gelu_pk(f32x2 v) {
;     const f32x2 av = __builtin_elementwise_abs(v), d = av * 0.2316418882f + 1.0f;
;     f32x2 t; t.x = __builtin_amdgcn_rcpf(d.x); t.y = __builtin_amdgcn_rcpf(d.y);
;     f32x2 q = t * 0.5307027145f + (-0.7265760135f); q = q * t + 0.7107068705f; q = q * t + (-0.142248368f); q = q * t + 0.127414796f; q = q * t;
;     const f32x2 s = (v * v) * (-0.72134752044f);
;     f32x2 e; e.x = __builtin_amdgcn_exp2f(s.x); e.y = __builtin_amdgcn_exp2f(s.y);
;     const f32x2 m = v * (q * e), r = v - m;
;     f32x2 o; o.x = v.x < 0.f ? m.x : r.x; o.y = v.y < 0.f ? m.y : r.y; return o;
; }
;     __device__ __forceinline__ void operator()(const f32x4 (&acc)[2][2][4][2], const Unit& u, int wr, int wc, int fr_, int fq_, int slot) const {
;     ...
;             for (int m = 0; m < 4; ++m) {
;                 const int row = u.pm * BM + ai * HALF + wr * 64 + m * 16 + fr;
;                 const float r = rs[ai][m];
;                 bf16_t* rowp = P + (size_t)row * ODD_IN + col0;
;                 float sq = 0.f;
; #pragma unroll
;                 for (int bj = 0; bj < 2; ++bj) {
;                     f32x4 v0 = acc[ai][bj][m][0] * r, v1 = acc[ai][bj][m][1] * r;
;                     if (pn >= 4 && pn < 8) { v0 = gelu4(v0); v1 = gelu4(v1); sq += sq4(v0) + sq4(v1); }
;                     *(u32x4*)(rowp + bj * HALF) = pack8(v0, v1);
;                 }
;                 if (pn >= 4 && pn < 8) { sq = fq_sum(sq); if (fq == 0) ssv[(size_t)row * 16 + (pn - 4) * 4 + wc] = sq; }
.LBB0_291:
	v_add_u32_e32 v96, 32, v132
	v_mov_b64_e32 v[98:99], s[0:1]
	v_mov_b32_e32 v110, v154
	v_mov_b32_e32 v111, v154
	v_add_u32_e32 v206, 32, v205
	v_mad_i64_i32 v[98:99], s[8:9], v206, s33, v[98:99]
	v_cvt_pk_bf16_f32 v106, v106, v107
	v_cvt_pk_bf16_f32 v107, v104, v105
	v_cvt_pk_bf16_f32 v108, v102, v103
	v_cvt_pk_bf16_f32 v109, v100, v101
	v_mov_b32_e32 v100, v154
	v_mov_b32_e32 v101, v154
	v_lshl_add_u64 v[98:99], v[130:131], 1, v[98:99]
	v_pk_mul_f32 v[94:95], v[94:95], v[100:101]
	v_pk_mul_f32 v[92:93], v[92:93], v[110:111]
	v_pk_mul_f32 v[90:91], v[90:91], v[100:101]
	s_and_b64 vcc, exec, s[42:43]
	v_pk_mul_f32 v[88:89], v[88:89], v[110:111]
	ds_write_b128 v203, v[106:109]
	ds_read_b128 v[106:109], v204
	s_waitcnt lgkmcnt(0)
	global_store_dwordx4 v[98:99], v[106:109], off
	s_cbranch_vccnz .LBB0_293
	s_nop 0
	v_and_b32_e32 v109, 0x7fffffff, v95
	v_and_b32_e32 v108, 0x7fffffff, v94
	v_pk_fma_f32 v[108:109], v[108:109], s[14:15], 1.0 op_sel_hi:[1,0,0]
	s_mov_b32 s8, 0xbf3a00e3
	v_rcp_f32_e32 v108, v108
	v_rcp_f32_e32 v109, v109
	v_mov_b64_e32 v[102:103], s[8:9]
	v_and_b32_e32 v101, 0x7fffffff, v93
	v_and_b32_e32 v100, 0x7fffffff, v92
	v_pk_fma_f32 v[110:111], v[108:109], s[34:35], v[102:103] op_sel_hi:[1,0,0]
	v_pk_fma_f32 v[100:101], v[100:101], s[14:15], 1.0 op_sel_hi:[1,0,0]
	v_pk_fma_f32 v[110:111], v[108:109], v[110:111], s[56:57] op_sel_hi:[1,1,0]
	v_rcp_f32_e32 v100, v100
	v_pk_fma_f32 v[110:111], v[108:109], v[110:111], s[10:11] op_sel_hi:[1,1,0]
	v_rcp_f32_e32 v101, v101
	v_pk_fma_f32 v[110:111], v[108:109], v[110:111], s[18:19] op_sel_hi:[1,1,0]
	v_and_b32_e32 v119, 0x7fffffff, v91
	v_pk_mul_f32 v[108:109], v[108:109], v[110:111]
	v_and_b32_e32 v111, 0x7fffffff, v89
	v_and_b32_e32 v110, 0x7fffffff, v88
	v_pk_fma_f32 v[110:111], v[110:111], s[14:15], 1.0 op_sel_hi:[1,0,0]
	v_and_b32_e32 v118, 0x7fffffff, v90
	v_rcp_f32_e32 v110, v110
	v_rcp_f32_e32 v111, v111
	v_pk_fma_f32 v[118:119], v[118:119], s[14:15], 1.0 op_sel_hi:[1,0,0]
	v_pk_mul_f32 v[116:117], v[88:89], v[88:89]
	v_rcp_f32_e32 v118, v118
	v_pk_fma_f32 v[114:115], v[110:111], s[34:35], v[102:103] op_sel_hi:[1,0,0]
	v_rcp_f32_e32 v119, v119
	v_pk_fma_f32 v[104:105], v[100:101], s[34:35], v[102:103] op_sel_hi:[1,0,0]
	v_pk_mul_f32 v[106:107], v[92:93], v[92:93]
	v_pk_fma_f32 v[114:115], v[110:111], v[114:115], s[56:57] op_sel_hi:[1,1,0]
	v_pk_mul_f32 v[116:117], v[116:117], s[12:13] op_sel_hi:[1,0]
	v_pk_fma_f32 v[104:105], v[100:101], v[104:105], s[56:57] op_sel_hi:[1,1,0]
	v_pk_mul_f32 v[106:107], v[106:107], s[12:13] op_sel_hi:[1,0]
	v_pk_fma_f32 v[114:115], v[110:111], v[114:115], s[10:11] op_sel_hi:[1,1,0]
	v_exp_f32_e32 v116, v116
	v_exp_f32_e32 v117, v117
	v_pk_fma_f32 v[104:105], v[100:101], v[104:105], s[10:11] op_sel_hi:[1,1,0]
	v_exp_f32_e32 v106, v106
	v_exp_f32_e32 v107, v107
	v_pk_fma_f32 v[114:115], v[110:111], v[114:115], s[18:19] op_sel_hi:[1,1,0]
	v_pk_fma_f32 v[104:105], v[100:101], v[104:105], s[18:19] op_sel_hi:[1,1,0]
	v_pk_mul_f32 v[110:111], v[110:111], v[114:115]
	v_pk_mul_f32 v[114:115], v[90:91], v[90:91]
	v_pk_fma_f32 v[102:103], v[118:119], s[34:35], v[102:103] op_sel_hi:[1,0,0]
	v_pk_mul_f32 v[100:101], v[100:101], v[104:105]
	v_pk_mul_f32 v[104:105], v[94:95], v[94:95]
	v_pk_fma_f32 v[102:103], v[118:119], v[102:103], s[56:57] op_sel_hi:[1,1,0]
	v_pk_mul_f32 v[114:115], v[114:115], s[12:13] op_sel_hi:[1,0]
	v_pk_mul_f32 v[104:105], v[104:105], s[12:13] op_sel_hi:[1,0]
	v_pk_mul_f32 v[110:111], v[116:117], v[110:111]
	v_exp_f32_e32 v114, v114
	v_exp_f32_e32 v115, v115
	v_pk_fma_f32 v[102:103], v[118:119], v[102:103], s[10:11] op_sel_hi:[1,1,0]
	v_pk_mul_f32 v[100:101], v[106:107], v[100:101]
	v_exp_f32_e32 v104, v104
	v_exp_f32_e32 v105, v105
	v_pk_mul_f32 v[116:117], v[88:89], v[110:111]
	v_pk_fma_f32 v[110:111], v[88:89], v[110:111], v[88:89] neg_lo:[1,0,0] neg_hi:[1,0,0]
	v_pk_fma_f32 v[102:103], v[118:119], v[102:103], s[18:19] op_sel_hi:[1,1,0]
	v_cmp_gt_f32_e32 vcc, 0, v88
	v_pk_mul_f32 v[106:107], v[92:93], v[100:101]
	v_pk_fma_f32 v[100:101], v[92:93], v[100:101], v[92:93] neg_lo:[1,0,0] neg_hi:[1,0,0]
	v_pk_mul_f32 v[102:103], v[118:119], v[102:103]
	v_cndmask_b32_e32 v119, v110, v116, vcc
	v_cmp_gt_f32_e32 vcc, 0, v92
	v_pk_mul_f32 v[102:103], v[114:115], v[102:103]
	v_pk_mul_f32 v[104:105], v[104:105], v[108:109]
	v_cndmask_b32_e32 v118, v100, v106, vcc
	v_cmp_gt_f32_e32 vcc, 0, v89
	v_pk_mul_f32 v[114:115], v[90:91], v[102:103]
	v_pk_fma_f32 v[102:103], v[90:91], v[102:103], v[90:91] neg_lo:[1,0,0] neg_hi:[1,0,0]
	v_cndmask_b32_e32 v89, v111, v117, vcc
	v_cmp_gt_f32_e32 vcc, 0, v93
	v_pk_mul_f32 v[108:109], v[94:95], v[104:105]
	v_pk_fma_f32 v[104:105], v[94:95], v[104:105], v[94:95] neg_lo:[1,0,0] neg_hi:[1,0,0]
	v_cndmask_b32_e32 v88, v101, v107, vcc
	v_cmp_gt_f32_e32 vcc, 0, v90
	v_pk_mul_f32 v[92:93], v[88:89], v[88:89]
	s_nop 0
	v_cndmask_b32_e32 v101, v102, v114, vcc
	v_cmp_gt_f32_e32 vcc, 0, v94
	v_pk_fma_f32 v[92:93], v[118:119], v[118:119], v[92:93]
	s_nop 0
	v_cndmask_b32_e32 v100, v104, v108, vcc
	v_cmp_gt_f32_e32 vcc, 0, v91
	s_nop 1
	v_cndmask_b32_e32 v91, v103, v115, vcc
	v_cmp_gt_f32_e32 vcc, 0, v95
	s_nop 1
	v_cndmask_b32_e32 v90, v105, v109, vcc
	v_pk_mul_f32 v[94:95], v[90:91], v[90:91]
	s_nop 0
	v_pk_fma_f32 v[94:95], v[100:101], v[100:101], v[94:95]
	s_nop 0
	v_pk_add_f32 v[92:93], v[92:93], v[94:95]
	v_mov_b32_e32 v94, v100
	v_add_f32_e32 v92, v92, v93
	v_add_f32_e32 v97, v92, v97
	v_mov_b32_e32 v92, v118
	v_mov_b32_e32 v93, v88
	v_mov_b32_e32 v95, v90
	v_mov_b32_e32 v88, v119
	v_mov_b32_e32 v90, v101
.LBB0_293:
	s_and_b64 vcc, exec, s[42:43]
	v_cvt_pk_bf16_f32 v92, v92, v93
	v_cvt_pk_bf16_f32 v93, v94, v95
	v_cvt_pk_bf16_f32 v94, v88, v89
	v_cvt_pk_bf16_f32 v95, v90, v91
	ds_write_b128 v203, v[92:95]
	ds_read_b128 v[92:95], v204
	s_waitcnt lgkmcnt(0)
	global_store_dwordx4 v[98:99], v[92:95], off offset:256
	s_cbranch_vccnz .LBB0_297
	v_mov_b32_e32 v88, v97
	s_nop 1
	v_permlane16_swap_b32_e32 v97, v88
	v_add_f32_e32 v88, v97, v88
	v_mov_b32_e32 v89, v88
	s_nop 1
	v_permlane32_swap_b32_e32 v88, v89
	s_and_saveexec_b64 s[92:93], s[44:45]
	s_cbranch_execz .LBB0_296
	v_ashrrev_i32_e32 v97, 31, v96
	v_readlane_b32 s8, v253, 6
	v_add_f32_e32 v90, v88, v89
	v_lshlrev_b64 v[88:89], 6, v[96:97]
	v_readlane_b32 s9, v253, 7
	s_nop 1
	v_lshl_add_u64 v[88:89], s[8:9], 0, v[88:89]
	v_lshl_add_u64 v[88:89], s[46:47], 2, v[88:89]
	s_lshl_b32 s8, s16, 2
	s_mov_b32 s9, s47
	v_lshl_add_u64 v[88:89], v[88:89], 0, s[8:9]
	global_store_dword v[88:89], v90, off offset:-64

; __device__ __forceinline__ f32x4 gelu4(f32x4 v) { f32x2 a = gelu_pk((f32x2){v[0], v[1]}), b = gelu_pk((f32x2){v[2], v[3]}); return (f32x4){a.x, a.y, b.x, b.y}; }
; __device__ __forceinline__ u32x4 pack8(f32x4 a, f32x4 b) { u32x4 w; w.x = cvt_pk_bf16(a[0], a[1]); w.y = cvt_pk_bf16(a[2], a[3]); w.z = cvt_pk_bf16(b[0], b[1]); w.w = cvt_pk_bf16(b[2], b[3]); return w; }
; __device__ __forceinline__ float sq4(f32x4 a) { return (a[0] * a[0] + a[1] * a[1]) + (a[2] * a[2] + a[3] * a[3]); }
; __device__ __forceinline__ f32x2 gelu_pk(f32x2 v) {
;     const f32x2 av = __builtin_elementwise_abs(v), d = av * 0.2316418882f + 1.0f;
;     f32x2 t; t.x = __builtin_amdgcn_rcpf(d.x); t.y = __builtin_amdgcn_rcpf(d.y);
;     f32x2 q = t * 0.5307027145f + (-0.7265760135f); q = q * t + 0.7107068705f; q = q * t + (-0.142248368f); q = q * t + 0.127414796f; q = q * t;
;     const f32x2 s = (v * v) * (-0.72134752044f);
;     f32x2 e; e.x = __builtin_amdgcn_exp2f(s.x); e.y = __builtin_amdgcn_exp2f(s.y);
;     const f32x2 m = v * (q * e), r = v - m;
;     f32x2 o; o.x = v.x < 0.f ? m.x : r.x; o.y = v.y < 0.f ? m.y : r.y; return o;
; }
;     __device__ __forceinline__ void operator()(const f32x4 (&acc)[2][2][4][2], const Unit& u, int wr, int wc, int fr_, int fq_, int slot) const {
;     ...
;             for (int m = 0; m < 4; ++m) {
;                 const int row = u.pm * BM + ai * HALF + wr * 64 + m * 16 + fr;
;                 const float r = rs[ai][m];
;                 bf16_t* rowp = P + (size_t)row * ODD_IN + col0;
;                 float sq = 0.f;
; #pragma unroll
;                 for (int bj = 0; bj < 2; ++bj) {
;                     f32x4 v0 = acc[ai][bj][m][0] * r, v1 = acc[ai][bj][m][1] * r;
;                     if (pn >= 4 && pn < 8) { v0 = gelu4(v0); v1 = gelu4(v1); sq += sq4(v0) + sq4(v1); }
;                     *(u32x4*)(rowp + bj * HALF) = pack8(v0, v1);
;                 }
;                 if (pn >= 4 && pn < 8) { sq = fq_sum(sq); if (fq == 0) ssv[(size_t)row * 16 + (pn - 4) * 4 + wc] = sq; }
.LBB0_299:
	v_add_u32_e32 v80, 48, v132
	v_mov_b64_e32 v[82:83], s[0:1]
	v_mov_b32_e32 v154, v155
	v_add_u32_e32 v206, 48, v205
	v_mad_i64_i32 v[82:83], s[8:9], v206, s33, v[82:83]
	v_cvt_pk_bf16_f32 v90, v90, v91
	v_cvt_pk_bf16_f32 v91, v88, v89
	v_cvt_pk_bf16_f32 v92, v86, v87
	v_cvt_pk_bf16_f32 v93, v84, v85
	v_mov_b32_e32 v84, v155
	v_mov_b32_e32 v85, v155
	v_lshl_add_u64 v[82:83], v[130:131], 1, v[82:83]
	v_pk_mul_f32 v[78:79], v[78:79], v[84:85]
	v_pk_mul_f32 v[76:77], v[76:77], v[154:155]
	v_pk_mul_f32 v[74:75], v[74:75], v[84:85]
	s_and_b64 vcc, exec, s[42:43]
	v_pk_mul_f32 v[72:73], v[72:73], v[154:155]
	ds_write_b128 v203, v[90:93]
	ds_read_b128 v[90:93], v204
	s_waitcnt lgkmcnt(0)
	global_store_dwordx4 v[82:83], v[90:93], off
	s_cbranch_vccnz .LBB0_301
	s_nop 0
	v_and_b32_e32 v93, 0x7fffffff, v79
	v_and_b32_e32 v92, 0x7fffffff, v78
	v_pk_fma_f32 v[92:93], v[92:93], s[14:15], 1.0 op_sel_hi:[1,0,0]
	s_mov_b32 s8, 0xbf3a00e3
	v_rcp_f32_e32 v92, v92
	v_rcp_f32_e32 v93, v93
	v_mov_b64_e32 v[86:87], s[8:9]
	v_and_b32_e32 v85, 0x7fffffff, v77
	v_and_b32_e32 v84, 0x7fffffff, v76
	v_pk_fma_f32 v[94:95], v[92:93], s[34:35], v[86:87] op_sel_hi:[1,0,0]
	v_pk_fma_f32 v[84:85], v[84:85], s[14:15], 1.0 op_sel_hi:[1,0,0]
	v_pk_fma_f32 v[94:95], v[92:93], v[94:95], s[56:57] op_sel_hi:[1,1,0]
	v_rcp_f32_e32 v84, v84
	v_pk_fma_f32 v[94:95], v[92:93], v[94:95], s[10:11] op_sel_hi:[1,1,0]
	v_rcp_f32_e32 v85, v85
	v_pk_fma_f32 v[94:95], v[92:93], v[94:95], s[18:19] op_sel_hi:[1,1,0]
	v_and_b32_e32 v101, 0x7fffffff, v75
	v_pk_mul_f32 v[92:93], v[92:93], v[94:95]
	v_and_b32_e32 v95, 0x7fffffff, v73
	v_and_b32_e32 v94, 0x7fffffff, v72
	v_pk_fma_f32 v[94:95], v[94:95], s[14:15], 1.0 op_sel_hi:[1,0,0]
	v_and_b32_e32 v100, 0x7fffffff, v74
	v_rcp_f32_e32 v94, v94
	v_rcp_f32_e32 v95, v95
	v_pk_fma_f32 v[100:101], v[100:101], s[14:15], 1.0 op_sel_hi:[1,0,0]
	v_pk_mul_f32 v[98:99], v[72:73], v[72:73]
	v_rcp_f32_e32 v100, v100
	v_pk_fma_f32 v[96:97], v[94:95], s[34:35], v[86:87] op_sel_hi:[1,0,0]
	v_rcp_f32_e32 v101, v101
	v_pk_fma_f32 v[88:89], v[84:85], s[34:35], v[86:87] op_sel_hi:[1,0,0]
	v_pk_mul_f32 v[90:91], v[76:77], v[76:77]
	v_pk_fma_f32 v[96:97], v[94:95], v[96:97], s[56:57] op_sel_hi:[1,1,0]
	v_pk_mul_f32 v[98:99], v[98:99], s[12:13] op_sel_hi:[1,0]
	v_pk_fma_f32 v[88:89], v[84:85], v[88:89], s[56:57] op_sel_hi:[1,1,0]
	v_pk_mul_f32 v[90:91], v[90:91], s[12:13] op_sel_hi:[1,0]
	v_pk_fma_f32 v[96:97], v[94:95], v[96:97], s[10:11] op_sel_hi:[1,1,0]
	v_exp_f32_e32 v98, v98
	v_exp_f32_e32 v99, v99
	v_pk_fma_f32 v[88:89], v[84:85], v[88:89], s[10:11] op_sel_hi:[1,1,0]
	v_exp_f32_e32 v90, v90
	v_exp_f32_e32 v91, v91
	v_pk_fma_f32 v[96:97], v[94:95], v[96:97], s[18:19] op_sel_hi:[1,1,0]
	v_pk_fma_f32 v[88:89], v[84:85], v[88:89], s[18:19] op_sel_hi:[1,1,0]
	v_pk_mul_f32 v[94:95], v[94:95], v[96:97]
	v_pk_mul_f32 v[96:97], v[74:75], v[74:75]
	v_pk_fma_f32 v[86:87], v[100:101], s[34:35], v[86:87] op_sel_hi:[1,0,0]
	v_pk_mul_f32 v[84:85], v[84:85], v[88:89]
	v_pk_mul_f32 v[88:89], v[78:79], v[78:79]
	v_pk_fma_f32 v[86:87], v[100:101], v[86:87], s[56:57] op_sel_hi:[1,1,0]
	v_pk_mul_f32 v[96:97], v[96:97], s[12:13] op_sel_hi:[1,0]
	v_pk_mul_f32 v[88:89], v[88:89], s[12:13] op_sel_hi:[1,0]
	v_pk_mul_f32 v[94:95], v[98:99], v[94:95]
	v_exp_f32_e32 v96, v96
	v_exp_f32_e32 v97, v97
	v_pk_fma_f32 v[86:87], v[100:101], v[86:87], s[10:11] op_sel_hi:[1,1,0]
	v_pk_mul_f32 v[84:85], v[90:91], v[84:85]
	v_exp_f32_e32 v88, v88
	v_exp_f32_e32 v89, v89
	v_pk_mul_f32 v[98:99], v[72:73], v[94:95]
	v_pk_fma_f32 v[94:95], v[72:73], v[94:95], v[72:73] neg_lo:[1,0,0] neg_hi:[1,0,0]
	v_pk_fma_f32 v[86:87], v[100:101], v[86:87], s[18:19] op_sel_hi:[1,1,0]
	v_cmp_gt_f32_e32 vcc, 0, v72
	v_pk_mul_f32 v[90:91], v[76:77], v[84:85]
	v_pk_fma_f32 v[84:85], v[76:77], v[84:85], v[76:77] neg_lo:[1,0,0] neg_hi:[1,0,0]
	v_pk_mul_f32 v[86:87], v[100:101], v[86:87]
	v_cndmask_b32_e32 v101, v94, v98, vcc
	v_cmp_gt_f32_e32 vcc, 0, v76
	v_pk_mul_f32 v[86:87], v[96:97], v[86:87]
	v_pk_mul_f32 v[88:89], v[88:89], v[92:93]
	v_cndmask_b32_e32 v100, v84, v90, vcc
	v_cmp_gt_f32_e32 vcc, 0, v73
	v_pk_mul_f32 v[96:97], v[74:75], v[86:87]
	v_pk_fma_f32 v[86:87], v[74:75], v[86:87], v[74:75] neg_lo:[1,0,0] neg_hi:[1,0,0]
	v_cndmask_b32_e32 v73, v95, v99, vcc
	v_cmp_gt_f32_e32 vcc, 0, v77
	v_pk_mul_f32 v[92:93], v[78:79], v[88:89]
	v_pk_fma_f32 v[88:89], v[78:79], v[88:89], v[78:79] neg_lo:[1,0,0] neg_hi:[1,0,0]
	v_cndmask_b32_e32 v72, v85, v91, vcc
	v_cmp_gt_f32_e32 vcc, 0, v74
	v_pk_mul_f32 v[76:77], v[72:73], v[72:73]
	s_nop 0
	v_cndmask_b32_e32 v85, v86, v96, vcc
	v_cmp_gt_f32_e32 vcc, 0, v78
	v_pk_fma_f32 v[76:77], v[100:101], v[100:101], v[76:77]
	s_nop 0
	v_cndmask_b32_e32 v84, v88, v92, vcc
	v_cmp_gt_f32_e32 vcc, 0, v75
	s_nop 1
	v_cndmask_b32_e32 v75, v87, v97, vcc
	v_cmp_gt_f32_e32 vcc, 0, v79
	s_nop 1
	v_cndmask_b32_e32 v74, v89, v93, vcc
	v_pk_mul_f32 v[78:79], v[74:75], v[74:75]
	s_nop 0
	v_pk_fma_f32 v[78:79], v[84:85], v[84:85], v[78:79]
	s_nop 0
	v_pk_add_f32 v[76:77], v[76:77], v[78:79]
	v_mov_b32_e32 v78, v84
	v_add_f32_e32 v76, v76, v77
	v_add_f32_e32 v81, v76, v81
	v_mov_b32_e32 v76, v100
	v_mov_b32_e32 v77, v72
	v_mov_b32_e32 v79, v74
	v_mov_b32_e32 v72, v101
	v_mov_b32_e32 v74, v85
.LBB0_301:
	s_and_b64 vcc, exec, s[42:43]
	v_cvt_pk_bf16_f32 v76, v76, v77
	v_cvt_pk_bf16_f32 v77, v78, v79
	v_cvt_pk_bf16_f32 v78, v72, v73
	v_cvt_pk_bf16_f32 v79, v74, v75
	ds_write_b128 v203, v[76:79]
	ds_read_b128 v[76:79], v204
	s_waitcnt lgkmcnt(0)
	global_store_dwordx4 v[82:83], v[76:79], off offset:256
	s_cbranch_vccnz .LBB0_305
	v_mov_b32_e32 v72, v81
	s_nop 1
	v_permlane16_swap_b32_e32 v81, v72
	v_add_f32_e32 v72, v81, v72
	v_mov_b32_e32 v73, v72
	s_nop 1
	v_permlane32_swap_b32_e32 v72, v73
	s_and_saveexec_b64 s[92:93], s[44:45]
	s_cbranch_execz .LBB0_304
	v_ashrrev_i32_e32 v81, 31, v80
	v_readlane_b32 s8, v253, 6
	v_add_f32_e32 v74, v72, v73
	v_lshlrev_b64 v[72:73], 6, v[80:81]
	v_readlane_b32 s9, v253, 7
	s_nop 1
	v_lshl_add_u64 v[72:73], s[8:9], 0, v[72:73]
	v_lshl_add_u64 v[72:73], s[46:47], 2, v[72:73]
	s_lshl_b32 s8, s16, 2
	s_mov_b32 s9, s47
	v_lshl_add_u64 v[72:73], v[72:73], 0, s[8:9]
	global_store_dword v[72:73], v74, off offset:-64

; __device__ __forceinline__ f32x4 gelu4(f32x4 v) { f32x2 a = gelu_pk((f32x2){v[0], v[1]}), b = gelu_pk((f32x2){v[2], v[3]}); return (f32x4){a.x, a.y, b.x, b.y}; }
; __device__ __forceinline__ u32x4 pack8(f32x4 a, f32x4 b) { u32x4 w; w.x = cvt_pk_bf16(a[0], a[1]); w.y = cvt_pk_bf16(a[2], a[3]); w.z = cvt_pk_bf16(b[0], b[1]); w.w = cvt_pk_bf16(b[2], b[3]); return w; }
; __device__ __forceinline__ float sq4(f32x4 a) { return (a[0] * a[0] + a[1] * a[1]) + (a[2] * a[2] + a[3] * a[3]); }
; __device__ __forceinline__ f32x2 gelu_pk(f32x2 v) {
;     const f32x2 av = __builtin_elementwise_abs(v), d = av * 0.2316418882f + 1.0f;
;     f32x2 t; t.x = __builtin_amdgcn_rcpf(d.x); t.y = __builtin_amdgcn_rcpf(d.y);
;     f32x2 q = t * 0.5307027145f + (-0.7265760135f); q = q * t + 0.7107068705f; q = q * t + (-0.142248368f); q = q * t + 0.127414796f; q = q * t;
;     const f32x2 s = (v * v) * (-0.72134752044f);
;     f32x2 e; e.x = __builtin_amdgcn_exp2f(s.x); e.y = __builtin_amdgcn_exp2f(s.y);
;     const f32x2 m = v * (q * e), r = v - m;
;     f32x2 o; o.x = v.x < 0.f ? m.x : r.x; o.y = v.y < 0.f ? m.y : r.y; return o;
; }
;     __device__ __forceinline__ void operator()(const f32x4 (&acc)[2][2][4][2], const Unit& u, int wr, int wc, int fr_, int fq_, int slot) const {
;     ...
;             for (int m = 0; m < 4; ++m) {
;                 const int row = u.pm * BM + ai * HALF + wr * 64 + m * 16 + fr;
;                 const float r = rs[ai][m];
;                 bf16_t* rowp = P + (size_t)row * ODD_IN + col0;
;                 float sq = 0.f;
; #pragma unroll
;                 for (int bj = 0; bj < 2; ++bj) {
;                     f32x4 v0 = acc[ai][bj][m][0] * r, v1 = acc[ai][bj][m][1] * r;
;                     if (pn >= 4 && pn < 8) { v0 = gelu4(v0); v1 = gelu4(v1); sq += sq4(v0) + sq4(v1); }
;                     *(u32x4*)(rowp + bj * HALF) = pack8(v0, v1);
;                 }
;                 if (pn >= 4 && pn < 8) { sq = fq_sum(sq); if (fq == 0) ssv[(size_t)row * 16 + (pn - 4) * 4 + wc] = sq; }
.LBB0_307:
	v_add_u32_e32 v64, 0x80, v132
	v_mov_b64_e32 v[66:67], s[0:1]
	v_mov_b32_e32 v78, v152
	v_mov_b32_e32 v79, v152
	v_add_u32_e32 v206, 0x80, v205
	v_mad_i64_i32 v[66:67], s[8:9], v206, s33, v[66:67]
	v_cvt_pk_bf16_f32 v74, v74, v75
	v_cvt_pk_bf16_f32 v75, v72, v73
	v_cvt_pk_bf16_f32 v76, v70, v71
	v_cvt_pk_bf16_f32 v77, v68, v69
	v_mov_b32_e32 v68, v152
	v_mov_b32_e32 v69, v152
	v_lshl_add_u64 v[66:67], v[130:131], 1, v[66:67]
	v_pk_mul_f32 v[62:63], v[62:63], v[68:69]
	v_pk_mul_f32 v[60:61], v[60:61], v[78:79]
	v_pk_mul_f32 v[58:59], v[58:59], v[68:69]
	s_and_b64 vcc, exec, s[42:43]
	v_pk_mul_f32 v[56:57], v[56:57], v[78:79]
	ds_write_b128 v203, v[74:77]
	ds_read_b128 v[74:77], v204
	s_waitcnt lgkmcnt(0)
	global_store_dwordx4 v[66:67], v[74:77], off
	s_cbranch_vccnz .LBB0_309
	s_nop 0
	v_and_b32_e32 v77, 0x7fffffff, v63
	v_and_b32_e32 v76, 0x7fffffff, v62
	v_pk_fma_f32 v[76:77], v[76:77], s[14:15], 1.0 op_sel_hi:[1,0,0]
	s_mov_b32 s8, 0xbf3a00e3
	v_rcp_f32_e32 v76, v76
	v_rcp_f32_e32 v77, v77
	v_mov_b64_e32 v[70:71], s[8:9]
	v_and_b32_e32 v69, 0x7fffffff, v61
	v_and_b32_e32 v68, 0x7fffffff, v60
	v_pk_fma_f32 v[78:79], v[76:77], s[34:35], v[70:71] op_sel_hi:[1,0,0]
	v_pk_fma_f32 v[68:69], v[68:69], s[14:15], 1.0 op_sel_hi:[1,0,0]
	v_pk_fma_f32 v[78:79], v[76:77], v[78:79], s[56:57] op_sel_hi:[1,1,0]
	v_rcp_f32_e32 v68, v68
	v_pk_fma_f32 v[78:79], v[76:77], v[78:79], s[10:11] op_sel_hi:[1,1,0]
	v_rcp_f32_e32 v69, v69
	v_pk_fma_f32 v[78:79], v[76:77], v[78:79], s[18:19] op_sel_hi:[1,1,0]
	v_and_b32_e32 v85, 0x7fffffff, v59
	v_pk_mul_f32 v[76:77], v[76:77], v[78:79]
	v_and_b32_e32 v79, 0x7fffffff, v57
	v_and_b32_e32 v78, 0x7fffffff, v56
	v_pk_fma_f32 v[78:79], v[78:79], s[14:15], 1.0 op_sel_hi:[1,0,0]
	v_and_b32_e32 v84, 0x7fffffff, v58
	v_rcp_f32_e32 v78, v78
	v_rcp_f32_e32 v79, v79
	v_pk_fma_f32 v[84:85], v[84:85], s[14:15], 1.0 op_sel_hi:[1,0,0]
	v_pk_mul_f32 v[82:83], v[56:57], v[56:57]
	v_rcp_f32_e32 v84, v84
	v_pk_fma_f32 v[80:81], v[78:79], s[34:35], v[70:71] op_sel_hi:[1,0,0]
	v_rcp_f32_e32 v85, v85
	v_pk_fma_f32 v[72:73], v[68:69], s[34:35], v[70:71] op_sel_hi:[1,0,0]
	v_pk_mul_f32 v[74:75], v[60:61], v[60:61]
	v_pk_fma_f32 v[80:81], v[78:79], v[80:81], s[56:57] op_sel_hi:[1,1,0]
	v_pk_mul_f32 v[82:83], v[82:83], s[12:13] op_sel_hi:[1,0]
	v_pk_fma_f32 v[72:73], v[68:69], v[72:73], s[56:57] op_sel_hi:[1,1,0]
	v_pk_mul_f32 v[74:75], v[74:75], s[12:13] op_sel_hi:[1,0]
	v_pk_fma_f32 v[80:81], v[78:79], v[80:81], s[10:11] op_sel_hi:[1,1,0]
	v_exp_f32_e32 v82, v82
	v_exp_f32_e32 v83, v83
	v_pk_fma_f32 v[72:73], v[68:69], v[72:73], s[10:11] op_sel_hi:[1,1,0]
	v_exp_f32_e32 v74, v74
	v_exp_f32_e32 v75, v75
	v_pk_fma_f32 v[80:81], v[78:79], v[80:81], s[18:19] op_sel_hi:[1,1,0]
	v_pk_fma_f32 v[72:73], v[68:69], v[72:73], s[18:19] op_sel_hi:[1,1,0]
	v_pk_mul_f32 v[78:79], v[78:79], v[80:81]
	v_pk_mul_f32 v[80:81], v[58:59], v[58:59]
	v_pk_fma_f32 v[70:71], v[84:85], s[34:35], v[70:71] op_sel_hi:[1,0,0]
	v_pk_mul_f32 v[68:69], v[68:69], v[72:73]
	v_pk_mul_f32 v[72:73], v[62:63], v[62:63]
	v_pk_fma_f32 v[70:71], v[84:85], v[70:71], s[56:57] op_sel_hi:[1,1,0]
	v_pk_mul_f32 v[80:81], v[80:81], s[12:13] op_sel_hi:[1,0]
	v_pk_mul_f32 v[72:73], v[72:73], s[12:13] op_sel_hi:[1,0]
	v_pk_mul_f32 v[78:79], v[82:83], v[78:79]
	v_exp_f32_e32 v80, v80
	v_exp_f32_e32 v81, v81
	v_pk_fma_f32 v[70:71], v[84:85], v[70:71], s[10:11] op_sel_hi:[1,1,0]
	v_pk_mul_f32 v[68:69], v[74:75], v[68:69]
	v_exp_f32_e32 v72, v72
	v_exp_f32_e32 v73, v73
	v_pk_mul_f32 v[82:83], v[56:57], v[78:79]
	v_pk_fma_f32 v[78:79], v[56:57], v[78:79], v[56:57] neg_lo:[1,0,0] neg_hi:[1,0,0]
	v_pk_fma_f32 v[70:71], v[84:85], v[70:71], s[18:19] op_sel_hi:[1,1,0]
	v_cmp_gt_f32_e32 vcc, 0, v56
	v_pk_mul_f32 v[74:75], v[60:61], v[68:69]
	v_pk_fma_f32 v[68:69], v[60:61], v[68:69], v[60:61] neg_lo:[1,0,0] neg_hi:[1,0,0]
	v_pk_mul_f32 v[70:71], v[84:85], v[70:71]
	v_cndmask_b32_e32 v85, v78, v82, vcc
	v_cmp_gt_f32_e32 vcc, 0, v60
	v_pk_mul_f32 v[70:71], v[80:81], v[70:71]
	v_pk_mul_f32 v[72:73], v[72:73], v[76:77]
	v_cndmask_b32_e32 v84, v68, v74, vcc
	v_cmp_gt_f32_e32 vcc, 0, v57
	v_pk_mul_f32 v[80:81], v[58:59], v[70:71]
	v_pk_fma_f32 v[70:71], v[58:59], v[70:71], v[58:59] neg_lo:[1,0,0] neg_hi:[1,0,0]
	v_cndmask_b32_e32 v57, v79, v83, vcc
	v_cmp_gt_f32_e32 vcc, 0, v61
	v_pk_mul_f32 v[76:77], v[62:63], v[72:73]
	v_pk_fma_f32 v[72:73], v[62:63], v[72:73], v[62:63] neg_lo:[1,0,0] neg_hi:[1,0,0]
	v_cndmask_b32_e32 v56, v69, v75, vcc
	v_cmp_gt_f32_e32 vcc, 0, v58
	v_pk_mul_f32 v[60:61], v[56:57], v[56:57]
	s_nop 0
	v_cndmask_b32_e32 v69, v70, v80, vcc
	v_cmp_gt_f32_e32 vcc, 0, v62
	v_pk_fma_f32 v[60:61], v[84:85], v[84:85], v[60:61]
	s_nop 0
	v_cndmask_b32_e32 v68, v72, v76, vcc
	v_cmp_gt_f32_e32 vcc, 0, v59
	s_nop 1
	v_cndmask_b32_e32 v59, v71, v81, vcc
	v_cmp_gt_f32_e32 vcc, 0, v63
	s_nop 1
	v_cndmask_b32_e32 v58, v73, v77, vcc
	v_pk_mul_f32 v[62:63], v[58:59], v[58:59]
	s_nop 0
	v_pk_fma_f32 v[62:63], v[68:69], v[68:69], v[62:63]
	s_nop 0
	v_pk_add_f32 v[60:61], v[60:61], v[62:63]
	v_mov_b32_e32 v62, v68
	v_add_f32_e32 v60, v60, v61
	v_add_f32_e32 v65, v60, v65
	v_mov_b32_e32 v60, v84
	v_mov_b32_e32 v61, v56
	v_mov_b32_e32 v63, v58
	v_mov_b32_e32 v56, v85
	v_mov_b32_e32 v58, v69
.LBB0_309:
	s_and_b64 vcc, exec, s[42:43]
	v_cvt_pk_bf16_f32 v60, v60, v61
	v_cvt_pk_bf16_f32 v61, v62, v63
	v_cvt_pk_bf16_f32 v62, v56, v57
	v_cvt_pk_bf16_f32 v63, v58, v59
	ds_write_b128 v203, v[60:63]
	ds_read_b128 v[60:63], v204
	s_waitcnt lgkmcnt(0)
	global_store_dwordx4 v[66:67], v[60:63], off offset:256
	s_cbranch_vccnz .LBB0_313
	v_mov_b32_e32 v56, v65
	s_nop 1
	v_permlane16_swap_b32_e32 v65, v56
	v_add_f32_e32 v56, v65, v56
	v_mov_b32_e32 v57, v56
	s_nop 1
	v_permlane32_swap_b32_e32 v56, v57
	s_and_saveexec_b64 s[92:93], s[44:45]
	s_cbranch_execz .LBB0_312
	v_ashrrev_i32_e32 v65, 31, v64
	v_readlane_b32 s8, v253, 6
	v_add_f32_e32 v58, v56, v57
	v_lshlrev_b64 v[56:57], 6, v[64:65]
	v_readlane_b32 s9, v253, 7
	s_nop 1
	v_lshl_add_u64 v[56:57], s[8:9], 0, v[56:57]
	v_lshl_add_u64 v[56:57], s[46:47], 2, v[56:57]
	s_lshl_b32 s8, s16, 2
	s_mov_b32 s9, s47
	v_lshl_add_u64 v[56:57], v[56:57], 0, s[8:9]
	global_store_dword v[56:57], v58, off offset:-64

; __device__ __forceinline__ f32x4 gelu4(f32x4 v) { f32x2 a = gelu_pk((f32x2){v[0], v[1]}), b = gelu_pk((f32x2){v[2], v[3]}); return (f32x4){a.x, a.y, b.x, b.y}; }
; __device__ __forceinline__ u32x4 pack8(f32x4 a, f32x4 b) { u32x4 w; w.x = cvt_pk_bf16(a[0], a[1]); w.y = cvt_pk_bf16(a[2], a[3]); w.z = cvt_pk_bf16(b[0], b[1]); w.w = cvt_pk_bf16(b[2], b[3]); return w; }
; __device__ __forceinline__ float sq4(f32x4 a) { return (a[0] * a[0] + a[1] * a[1]) + (a[2] * a[2] + a[3] * a[3]); }
; __device__ __forceinline__ f32x2 gelu_pk(f32x2 v) {
;     const f32x2 av = __builtin_elementwise_abs(v), d = av * 0.2316418882f + 1.0f;
;     f32x2 t; t.x = __builtin_amdgcn_rcpf(d.x); t.y = __builtin_amdgcn_rcpf(d.y);
;     f32x2 q = t * 0.5307027145f + (-0.7265760135f); q = q * t + 0.7107068705f; q = q * t + (-0.142248368f); q = q * t + 0.127414796f; q = q * t;
;     const f32x2 s = (v * v) * (-0.72134752044f);
;     f32x2 e; e.x = __builtin_amdgcn_exp2f(s.x); e.y = __builtin_amdgcn_exp2f(s.y);
;     const f32x2 m = v * (q * e), r = v - m;
;     f32x2 o; o.x = v.x < 0.f ? m.x : r.x; o.y = v.y < 0.f ? m.y : r.y; return o;
; }
;     __device__ __forceinline__ void operator()(const f32x4 (&acc)[2][2][4][2], const Unit& u, int wr, int wc, int fr_, int fq_, int slot) const {
;     ...
;             for (int m = 0; m < 4; ++m) {
;                 const int row = u.pm * BM + ai * HALF + wr * 64 + m * 16 + fr;
;                 const float r = rs[ai][m];
;                 bf16_t* rowp = P + (size_t)row * ODD_IN + col0;
;                 float sq = 0.f;
; #pragma unroll
;                 for (int bj = 0; bj < 2; ++bj) {
;                     f32x4 v0 = acc[ai][bj][m][0] * r, v1 = acc[ai][bj][m][1] * r;
;                     if (pn >= 4 && pn < 8) { v0 = gelu4(v0); v1 = gelu4(v1); sq += sq4(v0) + sq4(v1); }
;                     *(u32x4*)(rowp + bj * HALF) = pack8(v0, v1);
;                 }
;                 if (pn >= 4 && pn < 8) { sq = fq_sum(sq); if (fq == 0) ssv[(size_t)row * 16 + (pn - 4) * 4 + wc] = sq; }
.LBB0_315:
	v_add_u32_e32 v48, 0x90, v132
	v_mov_b64_e32 v[50:51], s[0:1]
	v_mov_b32_e32 v152, v153
	v_add_u32_e32 v206, 0x90, v205
	v_mad_i64_i32 v[50:51], s[8:9], v206, s33, v[50:51]
	v_cvt_pk_bf16_f32 v58, v58, v59
	v_cvt_pk_bf16_f32 v59, v56, v57
	v_cvt_pk_bf16_f32 v60, v54, v55
	v_cvt_pk_bf16_f32 v61, v52, v53
	v_mov_b32_e32 v52, v153
	v_mov_b32_e32 v53, v153
	v_lshl_add_u64 v[50:51], v[130:131], 1, v[50:51]
	v_pk_mul_f32 v[46:47], v[46:47], v[52:53]
	v_pk_mul_f32 v[44:45], v[44:45], v[152:153]
	v_pk_mul_f32 v[42:43], v[42:43], v[52:53]
	s_and_b64 vcc, exec, s[42:43]
	v_pk_mul_f32 v[40:41], v[40:41], v[152:153]
	ds_write_b128 v203, v[58:61]
	ds_read_b128 v[58:61], v204
	s_waitcnt lgkmcnt(0)
	global_store_dwordx4 v[50:51], v[58:61], off
	s_cbranch_vccnz .LBB0_317
	s_nop 0
	v_and_b32_e32 v61, 0x7fffffff, v47
	v_and_b32_e32 v60, 0x7fffffff, v46
	v_pk_fma_f32 v[60:61], v[60:61], s[14:15], 1.0 op_sel_hi:[1,0,0]
	s_mov_b32 s8, 0xbf3a00e3
	v_rcp_f32_e32 v60, v60
	v_rcp_f32_e32 v61, v61
	v_mov_b64_e32 v[54:55], s[8:9]
	v_and_b32_e32 v53, 0x7fffffff, v45
	v_and_b32_e32 v52, 0x7fffffff, v44
	v_pk_fma_f32 v[62:63], v[60:61], s[34:35], v[54:55] op_sel_hi:[1,0,0]
	v_pk_fma_f32 v[52:53], v[52:53], s[14:15], 1.0 op_sel_hi:[1,0,0]
	v_pk_fma_f32 v[62:63], v[60:61], v[62:63], s[56:57] op_sel_hi:[1,1,0]
	v_rcp_f32_e32 v52, v52
	v_pk_fma_f32 v[62:63], v[60:61], v[62:63], s[10:11] op_sel_hi:[1,1,0]
	v_rcp_f32_e32 v53, v53
	v_pk_fma_f32 v[62:63], v[60:61], v[62:63], s[18:19] op_sel_hi:[1,1,0]
	v_and_b32_e32 v69, 0x7fffffff, v43
	v_pk_mul_f32 v[60:61], v[60:61], v[62:63]
	v_and_b32_e32 v63, 0x7fffffff, v41
	v_and_b32_e32 v62, 0x7fffffff, v40
	v_pk_fma_f32 v[62:63], v[62:63], s[14:15], 1.0 op_sel_hi:[1,0,0]
	v_and_b32_e32 v68, 0x7fffffff, v42
	v_rcp_f32_e32 v62, v62
	v_rcp_f32_e32 v63, v63
	v_pk_fma_f32 v[68:69], v[68:69], s[14:15], 1.0 op_sel_hi:[1,0,0]
	v_pk_mul_f32 v[66:67], v[40:41], v[40:41]
	v_rcp_f32_e32 v68, v68
	v_pk_fma_f32 v[64:65], v[62:63], s[34:35], v[54:55] op_sel_hi:[1,0,0]
	v_rcp_f32_e32 v69, v69
	v_pk_fma_f32 v[56:57], v[52:53], s[34:35], v[54:55] op_sel_hi:[1,0,0]
	v_pk_mul_f32 v[58:59], v[44:45], v[44:45]
	v_pk_fma_f32 v[64:65], v[62:63], v[64:65], s[56:57] op_sel_hi:[1,1,0]
	v_pk_mul_f32 v[66:67], v[66:67], s[12:13] op_sel_hi:[1,0]
	v_pk_fma_f32 v[56:57], v[52:53], v[56:57], s[56:57] op_sel_hi:[1,1,0]
	v_pk_mul_f32 v[58:59], v[58:59], s[12:13] op_sel_hi:[1,0]
	v_pk_fma_f32 v[64:65], v[62:63], v[64:65], s[10:11] op_sel_hi:[1,1,0]
	v_exp_f32_e32 v66, v66
	v_exp_f32_e32 v67, v67
	v_pk_fma_f32 v[56:57], v[52:53], v[56:57], s[10:11] op_sel_hi:[1,1,0]
	v_exp_f32_e32 v58, v58
	v_exp_f32_e32 v59, v59
	v_pk_fma_f32 v[64:65], v[62:63], v[64:65], s[18:19] op_sel_hi:[1,1,0]
	v_pk_fma_f32 v[56:57], v[52:53], v[56:57], s[18:19] op_sel_hi:[1,1,0]
	v_pk_mul_f32 v[62:63], v[62:63], v[64:65]
	v_pk_mul_f32 v[64:65], v[42:43], v[42:43]
	v_pk_fma_f32 v[54:55], v[68:69], s[34:35], v[54:55] op_sel_hi:[1,0,0]
	v_pk_mul_f32 v[52:53], v[52:53], v[56:57]
	v_pk_mul_f32 v[56:57], v[46:47], v[46:47]
	v_pk_fma_f32 v[54:55], v[68:69], v[54:55], s[56:57] op_sel_hi:[1,1,0]
	v_pk_mul_f32 v[64:65], v[64:65], s[12:13] op_sel_hi:[1,0]
	v_pk_mul_f32 v[56:57], v[56:57], s[12:13] op_sel_hi:[1,0]
	v_pk_mul_f32 v[62:63], v[66:67], v[62:63]
	v_exp_f32_e32 v64, v64
	v_exp_f32_e32 v65, v65
	v_pk_fma_f32 v[54:55], v[68:69], v[54:55], s[10:11] op_sel_hi:[1,1,0]
	v_pk_mul_f32 v[52:53], v[58:59], v[52:53]
	v_exp_f32_e32 v56, v56
	v_exp_f32_e32 v57, v57
	v_pk_mul_f32 v[66:67], v[40:41], v[62:63]
	v_pk_fma_f32 v[62:63], v[40:41], v[62:63], v[40:41] neg_lo:[1,0,0] neg_hi:[1,0,0]
	v_pk_fma_f32 v[54:55], v[68:69], v[54:55], s[18:19] op_sel_hi:[1,1,0]
	v_cmp_gt_f32_e32 vcc, 0, v40
	v_pk_mul_f32 v[58:59], v[44:45], v[52:53]
	v_pk_fma_f32 v[52:53], v[44:45], v[52:53], v[44:45] neg_lo:[1,0,0] neg_hi:[1,0,0]
	v_pk_mul_f32 v[54:55], v[68:69], v[54:55]
	v_cndmask_b32_e32 v69, v62, v66, vcc
	v_cmp_gt_f32_e32 vcc, 0, v44
	v_pk_mul_f32 v[54:55], v[64:65], v[54:55]
	v_pk_mul_f32 v[56:57], v[56:57], v[60:61]
	v_cndmask_b32_e32 v68, v52, v58, vcc
	v_cmp_gt_f32_e32 vcc, 0, v41
	v_pk_mul_f32 v[64:65], v[42:43], v[54:55]
	v_pk_fma_f32 v[54:55], v[42:43], v[54:55], v[42:43] neg_lo:[1,0,0] neg_hi:[1,0,0]
	v_cndmask_b32_e32 v41, v63, v67, vcc
	v_cmp_gt_f32_e32 vcc, 0, v45
	v_pk_mul_f32 v[60:61], v[46:47], v[56:57]
	v_pk_fma_f32 v[56:57], v[46:47], v[56:57], v[46:47] neg_lo:[1,0,0] neg_hi:[1,0,0]
	v_cndmask_b32_e32 v40, v53, v59, vcc
	v_cmp_gt_f32_e32 vcc, 0, v42
	v_pk_mul_f32 v[44:45], v[40:41], v[40:41]
	s_nop 0
	v_cndmask_b32_e32 v53, v54, v64, vcc
	v_cmp_gt_f32_e32 vcc, 0, v46
	v_pk_fma_f32 v[44:45], v[68:69], v[68:69], v[44:45]
	s_nop 0
	v_cndmask_b32_e32 v52, v56, v60, vcc
	v_cmp_gt_f32_e32 vcc, 0, v43
	s_nop 1
	v_cndmask_b32_e32 v43, v55, v65, vcc
	v_cmp_gt_f32_e32 vcc, 0, v47
	s_nop 1
	v_cndmask_b32_e32 v42, v57, v61, vcc
	v_pk_mul_f32 v[46:47], v[42:43], v[42:43]
	s_nop 0
	v_pk_fma_f32 v[46:47], v[52:53], v[52:53], v[46:47]
	s_nop 0
	v_pk_add_f32 v[44:45], v[44:45], v[46:47]
	v_mov_b32_e32 v46, v52
	v_add_f32_e32 v44, v44, v45
	v_add_f32_e32 v49, v44, v49
	v_mov_b32_e32 v44, v68
	v_mov_b32_e32 v45, v40
	v_mov_b32_e32 v47, v42
	v_mov_b32_e32 v40, v69
	v_mov_b32_e32 v42, v53
.LBB0_317:
	s_and_b64 vcc, exec, s[42:43]
	v_cvt_pk_bf16_f32 v44, v44, v45
	v_cvt_pk_bf16_f32 v45, v46, v47
	v_cvt_pk_bf16_f32 v46, v40, v41
	v_cvt_pk_bf16_f32 v47, v42, v43
	ds_write_b128 v203, v[44:47]
	ds_read_b128 v[44:47], v204
	s_waitcnt lgkmcnt(0)
	global_store_dwordx4 v[50:51], v[44:47], off offset:256
	s_cbranch_vccnz .LBB0_321
	v_mov_b32_e32 v40, v49
	s_nop 1
	v_permlane16_swap_b32_e32 v49, v40
	v_add_f32_e32 v40, v49, v40
	v_mov_b32_e32 v41, v40
	s_nop 1
	v_permlane32_swap_b32_e32 v40, v41
	s_and_saveexec_b64 s[92:93], s[44:45]
	s_cbranch_execz .LBB0_320
	v_ashrrev_i32_e32 v49, 31, v48
	v_readlane_b32 s8, v253, 6
	v_add_f32_e32 v42, v40, v41
	v_lshlrev_b64 v[40:41], 6, v[48:49]
	v_readlane_b32 s9, v253, 7
	s_nop 1
	v_lshl_add_u64 v[40:41], s[8:9], 0, v[40:41]
	v_lshl_add_u64 v[40:41], s[46:47], 2, v[40:41]
	s_lshl_b32 s8, s16, 2
	s_mov_b32 s9, s47
	v_lshl_add_u64 v[40:41], v[40:41], 0, s[8:9]
	global_store_dword v[40:41], v42, off offset:-64

; __device__ __forceinline__ f32x4 gelu4(f32x4 v) { f32x2 a = gelu_pk((f32x2){v[0], v[1]}), b = gelu_pk((f32x2){v[2], v[3]}); return (f32x4){a.x, a.y, b.x, b.y}; }
; __device__ __forceinline__ u32x4 pack8(f32x4 a, f32x4 b) { u32x4 w; w.x = cvt_pk_bf16(a[0], a[1]); w.y = cvt_pk_bf16(a[2], a[3]); w.z = cvt_pk_bf16(b[0], b[1]); w.w = cvt_pk_bf16(b[2], b[3]); return w; }
; __device__ __forceinline__ float sq4(f32x4 a) { return (a[0] * a[0] + a[1] * a[1]) + (a[2] * a[2] + a[3] * a[3]); }
; __device__ __forceinline__ f32x2 gelu_pk(f32x2 v) {
;     const f32x2 av = __builtin_elementwise_abs(v), d = av * 0.2316418882f + 1.0f;
;     f32x2 t; t.x = __builtin_amdgcn_rcpf(d.x); t.y = __builtin_amdgcn_rcpf(d.y);
;     f32x2 q = t * 0.5307027145f + (-0.7265760135f); q = q * t + 0.7107068705f; q = q * t + (-0.142248368f); q = q * t + 0.127414796f; q = q * t;
;     const f32x2 s = (v * v) * (-0.72134752044f);
;     f32x2 e; e.x = __builtin_amdgcn_exp2f(s.x); e.y = __builtin_amdgcn_exp2f(s.y);
;     const f32x2 m = v * (q * e), r = v - m;
;     f32x2 o; o.x = v.x < 0.f ? m.x : r.x; o.y = v.y < 0.f ? m.y : r.y; return o;
; }
;     __device__ __forceinline__ void operator()(const f32x4 (&acc)[2][2][4][2], const Unit& u, int wr, int wc, int fr_, int fq_, int slot) const {
;     ...
;             for (int m = 0; m < 4; ++m) {
;                 const int row = u.pm * BM + ai * HALF + wr * 64 + m * 16 + fr;
;                 const float r = rs[ai][m];
;                 bf16_t* rowp = P + (size_t)row * ODD_IN + col0;
;                 float sq = 0.f;
; #pragma unroll
;                 for (int bj = 0; bj < 2; ++bj) {
;                     f32x4 v0 = acc[ai][bj][m][0] * r, v1 = acc[ai][bj][m][1] * r;
;                     if (pn >= 4 && pn < 8) { v0 = gelu4(v0); v1 = gelu4(v1); sq += sq4(v0) + sq4(v1); }
;                     *(u32x4*)(rowp + bj * HALF) = pack8(v0, v1);
;                 }
;                 if (pn >= 4 && pn < 8) { sq = fq_sum(sq); if (fq == 0) ssv[(size_t)row * 16 + (pn - 4) * 4 + wc] = sq; }
.LBB0_323:
	v_add_u32_e32 v32, 0xa0, v132
	v_mov_b64_e32 v[34:35], s[0:1]
	v_mov_b32_e32 v46, v150
	v_mov_b32_e32 v47, v150
	v_add_u32_e32 v206, 0xa0, v205
	v_mad_i64_i32 v[34:35], s[8:9], v206, s33, v[34:35]
	v_cvt_pk_bf16_f32 v42, v42, v43
	v_cvt_pk_bf16_f32 v43, v40, v41
	v_cvt_pk_bf16_f32 v44, v38, v39
	v_cvt_pk_bf16_f32 v45, v36, v37
	v_mov_b32_e32 v36, v150
	v_mov_b32_e32 v37, v150
	v_lshl_add_u64 v[34:35], v[130:131], 1, v[34:35]
	v_pk_mul_f32 v[30:31], v[30:31], v[36:37]
	v_pk_mul_f32 v[28:29], v[28:29], v[46:47]
	v_pk_mul_f32 v[26:27], v[26:27], v[36:37]
	s_and_b64 vcc, exec, s[42:43]
	v_pk_mul_f32 v[24:25], v[24:25], v[46:47]
	ds_write_b128 v203, v[42:45]
	ds_read_b128 v[42:45], v204
	s_waitcnt lgkmcnt(0)
	global_store_dwordx4 v[34:35], v[42:45], off
	s_cbranch_vccnz .LBB0_325
	s_nop 0
	v_and_b32_e32 v45, 0x7fffffff, v31
	v_and_b32_e32 v44, 0x7fffffff, v30
	v_pk_fma_f32 v[44:45], v[44:45], s[14:15], 1.0 op_sel_hi:[1,0,0]
	s_mov_b32 s8, 0xbf3a00e3
	v_rcp_f32_e32 v44, v44
	v_rcp_f32_e32 v45, v45
	v_mov_b64_e32 v[38:39], s[8:9]
	v_and_b32_e32 v37, 0x7fffffff, v29
	v_and_b32_e32 v36, 0x7fffffff, v28
	v_pk_fma_f32 v[46:47], v[44:45], s[34:35], v[38:39] op_sel_hi:[1,0,0]
	v_pk_fma_f32 v[36:37], v[36:37], s[14:15], 1.0 op_sel_hi:[1,0,0]
	v_pk_fma_f32 v[46:47], v[44:45], v[46:47], s[56:57] op_sel_hi:[1,1,0]
	v_rcp_f32_e32 v36, v36
	v_pk_fma_f32 v[46:47], v[44:45], v[46:47], s[10:11] op_sel_hi:[1,1,0]
	v_rcp_f32_e32 v37, v37
	v_pk_fma_f32 v[46:47], v[44:45], v[46:47], s[18:19] op_sel_hi:[1,1,0]
	v_and_b32_e32 v53, 0x7fffffff, v27
	v_pk_mul_f32 v[44:45], v[44:45], v[46:47]
	v_and_b32_e32 v47, 0x7fffffff, v25
	v_and_b32_e32 v46, 0x7fffffff, v24
	v_pk_fma_f32 v[46:47], v[46:47], s[14:15], 1.0 op_sel_hi:[1,0,0]
	v_and_b32_e32 v52, 0x7fffffff, v26
	v_rcp_f32_e32 v46, v46
	v_rcp_f32_e32 v47, v47
	v_pk_fma_f32 v[52:53], v[52:53], s[14:15], 1.0 op_sel_hi:[1,0,0]
	v_pk_mul_f32 v[50:51], v[24:25], v[24:25]
	v_rcp_f32_e32 v52, v52
	v_pk_fma_f32 v[48:49], v[46:47], s[34:35], v[38:39] op_sel_hi:[1,0,0]
	v_rcp_f32_e32 v53, v53
	v_pk_fma_f32 v[40:41], v[36:37], s[34:35], v[38:39] op_sel_hi:[1,0,0]
	v_pk_mul_f32 v[42:43], v[28:29], v[28:29]
	v_pk_fma_f32 v[48:49], v[46:47], v[48:49], s[56:57] op_sel_hi:[1,1,0]
	v_pk_mul_f32 v[50:51], v[50:51], s[12:13] op_sel_hi:[1,0]
	v_pk_fma_f32 v[40:41], v[36:37], v[40:41], s[56:57] op_sel_hi:[1,1,0]
	v_pk_mul_f32 v[42:43], v[42:43], s[12:13] op_sel_hi:[1,0]
	v_pk_fma_f32 v[48:49], v[46:47], v[48:49], s[10:11] op_sel_hi:[1,1,0]
	v_exp_f32_e32 v50, v50
	v_exp_f32_e32 v51, v51
	v_pk_fma_f32 v[40:41], v[36:37], v[40:41], s[10:11] op_sel_hi:[1,1,0]
	v_exp_f32_e32 v42, v42
	v_exp_f32_e32 v43, v43
	v_pk_fma_f32 v[48:49], v[46:47], v[48:49], s[18:19] op_sel_hi:[1,1,0]
	v_pk_fma_f32 v[40:41], v[36:37], v[40:41], s[18:19] op_sel_hi:[1,1,0]
	v_pk_mul_f32 v[46:47], v[46:47], v[48:49]
	v_pk_mul_f32 v[48:49], v[26:27], v[26:27]
	v_pk_fma_f32 v[38:39], v[52:53], s[34:35], v[38:39] op_sel_hi:[1,0,0]
	v_pk_mul_f32 v[36:37], v[36:37], v[40:41]
	v_pk_mul_f32 v[40:41], v[30:31], v[30:31]
	v_pk_fma_f32 v[38:39], v[52:53], v[38:39], s[56:57] op_sel_hi:[1,1,0]
	v_pk_mul_f32 v[48:49], v[48:49], s[12:13] op_sel_hi:[1,0]
	v_pk_mul_f32 v[40:41], v[40:41], s[12:13] op_sel_hi:[1,0]
	v_pk_mul_f32 v[46:47], v[50:51], v[46:47]
	v_exp_f32_e32 v48, v48
	v_exp_f32_e32 v49, v49
	v_pk_fma_f32 v[38:39], v[52:53], v[38:39], s[10:11] op_sel_hi:[1,1,0]
	v_pk_mul_f32 v[36:37], v[42:43], v[36:37]
	v_exp_f32_e32 v40, v40
	v_exp_f32_e32 v41, v41
	v_pk_mul_f32 v[50:51], v[24:25], v[46:47]
	v_pk_fma_f32 v[46:47], v[24:25], v[46:47], v[24:25] neg_lo:[1,0,0] neg_hi:[1,0,0]
	v_pk_fma_f32 v[38:39], v[52:53], v[38:39], s[18:19] op_sel_hi:[1,1,0]
	v_cmp_gt_f32_e32 vcc, 0, v24
	v_pk_mul_f32 v[42:43], v[28:29], v[36:37]
	v_pk_fma_f32 v[36:37], v[28:29], v[36:37], v[28:29] neg_lo:[1,0,0] neg_hi:[1,0,0]
	v_pk_mul_f32 v[38:39], v[52:53], v[38:39]
	v_cndmask_b32_e32 v53, v46, v50, vcc
	v_cmp_gt_f32_e32 vcc, 0, v28
	v_pk_mul_f32 v[38:39], v[48:49], v[38:39]
	v_pk_mul_f32 v[40:41], v[40:41], v[44:45]
	v_cndmask_b32_e32 v52, v36, v42, vcc
	v_cmp_gt_f32_e32 vcc, 0, v25
	v_pk_mul_f32 v[48:49], v[26:27], v[38:39]
	v_pk_fma_f32 v[38:39], v[26:27], v[38:39], v[26:27] neg_lo:[1,0,0] neg_hi:[1,0,0]
	v_cndmask_b32_e32 v25, v47, v51, vcc
	v_cmp_gt_f32_e32 vcc, 0, v29
	v_pk_mul_f32 v[44:45], v[30:31], v[40:41]
	v_pk_fma_f32 v[40:41], v[30:31], v[40:41], v[30:31] neg_lo:[1,0,0] neg_hi:[1,0,0]
	v_cndmask_b32_e32 v24, v37, v43, vcc
	v_cmp_gt_f32_e32 vcc, 0, v26
	v_pk_mul_f32 v[28:29], v[24:25], v[24:25]
	s_nop 0
	v_cndmask_b32_e32 v37, v38, v48, vcc
	v_cmp_gt_f32_e32 vcc, 0, v30
	v_pk_fma_f32 v[28:29], v[52:53], v[52:53], v[28:29]
	s_nop 0
	v_cndmask_b32_e32 v36, v40, v44, vcc
	v_cmp_gt_f32_e32 vcc, 0, v27
	s_nop 1
	v_cndmask_b32_e32 v27, v39, v49, vcc
	v_cmp_gt_f32_e32 vcc, 0, v31
	s_nop 1
	v_cndmask_b32_e32 v26, v41, v45, vcc
	v_pk_mul_f32 v[30:31], v[26:27], v[26:27]
	s_nop 0
	v_pk_fma_f32 v[30:31], v[36:37], v[36:37], v[30:31]
	s_nop 0
	v_pk_add_f32 v[28:29], v[28:29], v[30:31]
	v_mov_b32_e32 v30, v36
	v_add_f32_e32 v28, v28, v29
	v_add_f32_e32 v33, v28, v33
	v_mov_b32_e32 v28, v52
	v_mov_b32_e32 v29, v24
	v_mov_b32_e32 v31, v26
	v_mov_b32_e32 v24, v53
	v_mov_b32_e32 v26, v37
.LBB0_325:
	s_and_b64 vcc, exec, s[42:43]
	v_cvt_pk_bf16_f32 v28, v28, v29
	v_cvt_pk_bf16_f32 v29, v30, v31
	v_cvt_pk_bf16_f32 v30, v24, v25
	v_cvt_pk_bf16_f32 v31, v26, v27
	ds_write_b128 v203, v[28:31]
	ds_read_b128 v[28:31], v204
	s_waitcnt lgkmcnt(0)
	global_store_dwordx4 v[34:35], v[28:31], off offset:256
	s_cbranch_vccnz .LBB0_329
	v_mov_b32_e32 v24, v33
	s_nop 1
	v_permlane16_swap_b32_e32 v33, v24
	v_add_f32_e32 v24, v33, v24
	v_mov_b32_e32 v25, v24
	s_nop 1
	v_permlane32_swap_b32_e32 v24, v25
	s_and_saveexec_b64 s[92:93], s[44:45]
	s_cbranch_execz .LBB0_328
	v_ashrrev_i32_e32 v33, 31, v32
	v_readlane_b32 s8, v253, 6
	v_add_f32_e32 v26, v24, v25
	v_lshlrev_b64 v[24:25], 6, v[32:33]
	v_readlane_b32 s9, v253, 7
	s_nop 1
	v_lshl_add_u64 v[24:25], s[8:9], 0, v[24:25]
	v_lshl_add_u64 v[24:25], s[46:47], 2, v[24:25]
	s_lshl_b32 s8, s16, 2
	s_mov_b32 s9, s47
	v_lshl_add_u64 v[24:25], v[24:25], 0, s[8:9]
	global_store_dword v[24:25], v26, off offset:-64

; __device__ __forceinline__ f32x4 gelu4(f32x4 v) { f32x2 a = gelu_pk((f32x2){v[0], v[1]}), b = gelu_pk((f32x2){v[2], v[3]}); return (f32x4){a.x, a.y, b.x, b.y}; }
; __device__ __forceinline__ u32x4 pack8(f32x4 a, f32x4 b) { u32x4 w; w.x = cvt_pk_bf16(a[0], a[1]); w.y = cvt_pk_bf16(a[2], a[3]); w.z = cvt_pk_bf16(b[0], b[1]); w.w = cvt_pk_bf16(b[2], b[3]); return w; }
; __device__ __forceinline__ float sq4(f32x4 a) { return (a[0] * a[0] + a[1] * a[1]) + (a[2] * a[2] + a[3] * a[3]); }
; __device__ __forceinline__ f32x2 gelu_pk(f32x2 v) {
;     const f32x2 av = __builtin_elementwise_abs(v), d = av * 0.2316418882f + 1.0f;
;     f32x2 t; t.x = __builtin_amdgcn_rcpf(d.x); t.y = __builtin_amdgcn_rcpf(d.y);
;     f32x2 q = t * 0.5307027145f + (-0.7265760135f); q = q * t + 0.7107068705f; q = q * t + (-0.142248368f); q = q * t + 0.127414796f; q = q * t;
;     const f32x2 s = (v * v) * (-0.72134752044f);
;     f32x2 e; e.x = __builtin_amdgcn_exp2f(s.x); e.y = __builtin_amdgcn_exp2f(s.y);
;     const f32x2 m = v * (q * e), r = v - m;
;     f32x2 o; o.x = v.x < 0.f ? m.x : r.x; o.y = v.y < 0.f ? m.y : r.y; return o;
; }
;     __device__ __forceinline__ void operator()(const f32x4 (&acc)[2][2][4][2], const Unit& u, int wr, int wc, int fr_, int fq_, int slot) const {
;     ...
;             for (int m = 0; m < 4; ++m) {
;                 const int row = u.pm * BM + ai * HALF + wr * 64 + m * 16 + fr;
;                 const float r = rs[ai][m];
;                 bf16_t* rowp = P + (size_t)row * ODD_IN + col0;
;                 float sq = 0.f;
; #pragma unroll
;                 for (int bj = 0; bj < 2; ++bj) {
;                     f32x4 v0 = acc[ai][bj][m][0] * r, v1 = acc[ai][bj][m][1] * r;
;                     if (pn >= 4 && pn < 8) { v0 = gelu4(v0); v1 = gelu4(v1); sq += sq4(v0) + sq4(v1); }
;                     *(u32x4*)(rowp + bj * HALF) = pack8(v0, v1);
;                 }
;                 if (pn >= 4 && pn < 8) { sq = fq_sum(sq); if (fq == 0) ssv[(size_t)row * 16 + (pn - 4) * 4 + wc] = sq; }
.LBB0_331:
	v_add_u32_e32 v16, 0xb0, v132
	v_mov_b64_e32 v[18:19], s[0:1]
	v_mov_b32_e32 v150, v151
	v_add_u32_e32 v206, 0xb0, v205
	v_mad_i64_i32 v[18:19], s[8:9], v206, s33, v[18:19]
	v_cvt_pk_bf16_f32 v26, v26, v27
	v_cvt_pk_bf16_f32 v27, v24, v25
	v_cvt_pk_bf16_f32 v28, v22, v23
	v_cvt_pk_bf16_f32 v29, v20, v21
	v_mov_b32_e32 v20, v151
	v_mov_b32_e32 v21, v151
	v_lshl_add_u64 v[18:19], v[130:131], 1, v[18:19]
	v_pk_mul_f32 v[14:15], v[14:15], v[20:21]
	v_pk_mul_f32 v[12:13], v[12:13], v[150:151]
	v_pk_mul_f32 v[10:11], v[10:11], v[20:21]
	s_and_b64 vcc, exec, s[42:43]
	v_pk_mul_f32 v[8:9], v[8:9], v[150:151]
	ds_write_b128 v203, v[26:29]
	ds_read_b128 v[26:29], v204
	s_waitcnt lgkmcnt(0)
	global_store_dwordx4 v[18:19], v[26:29], off
	s_cbranch_vccnz .LBB0_333
	s_nop 0
	v_and_b32_e32 v29, 0x7fffffff, v15
	v_and_b32_e32 v28, 0x7fffffff, v14
	v_pk_fma_f32 v[28:29], v[28:29], s[14:15], 1.0 op_sel_hi:[1,0,0]
	s_mov_b32 s8, 0xbf3a00e3
	v_rcp_f32_e32 v28, v28
	v_rcp_f32_e32 v29, v29
	v_mov_b64_e32 v[22:23], s[8:9]
	v_and_b32_e32 v21, 0x7fffffff, v13
	v_and_b32_e32 v20, 0x7fffffff, v12
	v_pk_fma_f32 v[30:31], v[28:29], s[34:35], v[22:23] op_sel_hi:[1,0,0]
	v_pk_fma_f32 v[20:21], v[20:21], s[14:15], 1.0 op_sel_hi:[1,0,0]
	v_pk_fma_f32 v[30:31], v[28:29], v[30:31], s[56:57] op_sel_hi:[1,1,0]
	v_rcp_f32_e32 v20, v20
	v_pk_fma_f32 v[30:31], v[28:29], v[30:31], s[10:11] op_sel_hi:[1,1,0]
	v_rcp_f32_e32 v21, v21
	v_pk_fma_f32 v[30:31], v[28:29], v[30:31], s[18:19] op_sel_hi:[1,1,0]
	v_and_b32_e32 v37, 0x7fffffff, v11
	v_pk_mul_f32 v[28:29], v[28:29], v[30:31]
	v_and_b32_e32 v31, 0x7fffffff, v9
	v_and_b32_e32 v30, 0x7fffffff, v8
	v_pk_fma_f32 v[30:31], v[30:31], s[14:15], 1.0 op_sel_hi:[1,0,0]
	v_and_b32_e32 v36, 0x7fffffff, v10
	v_rcp_f32_e32 v30, v30
	v_rcp_f32_e32 v31, v31
	v_pk_fma_f32 v[36:37], v[36:37], s[14:15], 1.0 op_sel_hi:[1,0,0]
	v_pk_mul_f32 v[34:35], v[8:9], v[8:9]
	v_rcp_f32_e32 v36, v36
	v_pk_fma_f32 v[32:33], v[30:31], s[34:35], v[22:23] op_sel_hi:[1,0,0]
	v_rcp_f32_e32 v37, v37
	v_pk_fma_f32 v[24:25], v[20:21], s[34:35], v[22:23] op_sel_hi:[1,0,0]
	v_pk_mul_f32 v[26:27], v[12:13], v[12:13]
	v_pk_fma_f32 v[32:33], v[30:31], v[32:33], s[56:57] op_sel_hi:[1,1,0]
	v_pk_mul_f32 v[34:35], v[34:35], s[12:13] op_sel_hi:[1,0]
	v_pk_fma_f32 v[24:25], v[20:21], v[24:25], s[56:57] op_sel_hi:[1,1,0]
	v_pk_mul_f32 v[26:27], v[26:27], s[12:13] op_sel_hi:[1,0]
	v_pk_fma_f32 v[32:33], v[30:31], v[32:33], s[10:11] op_sel_hi:[1,1,0]
	v_exp_f32_e32 v34, v34
	v_exp_f32_e32 v35, v35
	v_pk_fma_f32 v[24:25], v[20:21], v[24:25], s[10:11] op_sel_hi:[1,1,0]
	v_exp_f32_e32 v26, v26
	v_exp_f32_e32 v27, v27
	v_pk_fma_f32 v[32:33], v[30:31], v[32:33], s[18:19] op_sel_hi:[1,1,0]
	v_pk_fma_f32 v[24:25], v[20:21], v[24:25], s[18:19] op_sel_hi:[1,1,0]
	v_pk_mul_f32 v[30:31], v[30:31], v[32:33]
	v_pk_mul_f32 v[32:33], v[10:11], v[10:11]
	v_pk_fma_f32 v[22:23], v[36:37], s[34:35], v[22:23] op_sel_hi:[1,0,0]
	v_pk_mul_f32 v[20:21], v[20:21], v[24:25]
	v_pk_mul_f32 v[24:25], v[14:15], v[14:15]
	v_pk_fma_f32 v[22:23], v[36:37], v[22:23], s[56:57] op_sel_hi:[1,1,0]
	v_pk_mul_f32 v[32:33], v[32:33], s[12:13] op_sel_hi:[1,0]
	v_pk_mul_f32 v[24:25], v[24:25], s[12:13] op_sel_hi:[1,0]
	v_pk_mul_f32 v[30:31], v[34:35], v[30:31]
	v_exp_f32_e32 v32, v32
	v_exp_f32_e32 v33, v33
	v_pk_fma_f32 v[22:23], v[36:37], v[22:23], s[10:11] op_sel_hi:[1,1,0]
	v_pk_mul_f32 v[20:21], v[26:27], v[20:21]
	v_exp_f32_e32 v24, v24
	v_exp_f32_e32 v25, v25
	v_pk_mul_f32 v[34:35], v[8:9], v[30:31]
	v_pk_fma_f32 v[30:31], v[8:9], v[30:31], v[8:9] neg_lo:[1,0,0] neg_hi:[1,0,0]
	v_pk_fma_f32 v[22:23], v[36:37], v[22:23], s[18:19] op_sel_hi:[1,1,0]
	v_cmp_gt_f32_e32 vcc, 0, v8
	v_pk_mul_f32 v[26:27], v[12:13], v[20:21]
	v_pk_fma_f32 v[20:21], v[12:13], v[20:21], v[12:13] neg_lo:[1,0,0] neg_hi:[1,0,0]
	v_pk_mul_f32 v[22:23], v[36:37], v[22:23]
	v_cndmask_b32_e32 v37, v30, v34, vcc
	v_cmp_gt_f32_e32 vcc, 0, v12
	v_pk_mul_f32 v[22:23], v[32:33], v[22:23]
	v_pk_mul_f32 v[24:25], v[24:25], v[28:29]
	v_cndmask_b32_e32 v36, v20, v26, vcc
	v_cmp_gt_f32_e32 vcc, 0, v9
	v_pk_mul_f32 v[32:33], v[10:11], v[22:23]
	v_pk_fma_f32 v[22:23], v[10:11], v[22:23], v[10:11] neg_lo:[1,0,0] neg_hi:[1,0,0]
	v_cndmask_b32_e32 v9, v31, v35, vcc
	v_cmp_gt_f32_e32 vcc, 0, v13
	v_pk_mul_f32 v[28:29], v[14:15], v[24:25]
	v_pk_fma_f32 v[24:25], v[14:15], v[24:25], v[14:15] neg_lo:[1,0,0] neg_hi:[1,0,0]
	v_cndmask_b32_e32 v8, v21, v27, vcc
	v_cmp_gt_f32_e32 vcc, 0, v10
	v_pk_mul_f32 v[12:13], v[8:9], v[8:9]
	s_nop 0
	v_cndmask_b32_e32 v21, v22, v32, vcc
	v_cmp_gt_f32_e32 vcc, 0, v14
	v_pk_fma_f32 v[12:13], v[36:37], v[36:37], v[12:13]
	s_nop 0
	v_cndmask_b32_e32 v20, v24, v28, vcc
	v_cmp_gt_f32_e32 vcc, 0, v11
	s_nop 1
	v_cndmask_b32_e32 v11, v23, v33, vcc
	v_cmp_gt_f32_e32 vcc, 0, v15
	s_nop 1
	v_cndmask_b32_e32 v10, v25, v29, vcc
	v_pk_mul_f32 v[14:15], v[10:11], v[10:11]
	s_nop 0
	v_pk_fma_f32 v[14:15], v[20:21], v[20:21], v[14:15]
	s_nop 0
	v_pk_add_f32 v[12:13], v[12:13], v[14:15]
	v_mov_b32_e32 v14, v20
	v_add_f32_e32 v12, v12, v13
	v_add_f32_e32 v17, v12, v17
	v_mov_b32_e32 v12, v36
	v_mov_b32_e32 v13, v8
	v_mov_b32_e32 v15, v10
	v_mov_b32_e32 v8, v37
	v_mov_b32_e32 v10, v21
.LBB0_333:
	s_and_b64 vcc, exec, s[42:43]
	v_cvt_pk_bf16_f32 v12, v12, v13
	v_cvt_pk_bf16_f32 v13, v14, v15
	v_cvt_pk_bf16_f32 v14, v8, v9
	v_cvt_pk_bf16_f32 v15, v10, v11
	ds_write_b128 v203, v[12:15]
	ds_read_b128 v[12:15], v204
	s_waitcnt lgkmcnt(0)
	global_store_dwordx4 v[18:19], v[12:15], off offset:256
	s_cbranch_vccnz .LBB0_337
	v_mov_b32_e32 v8, v17
	s_nop 1
	v_permlane16_swap_b32_e32 v17, v8
	v_add_f32_e32 v8, v17, v8
	v_mov_b32_e32 v9, v8
	s_nop 1
	v_permlane32_swap_b32_e32 v8, v9
	s_and_saveexec_b64 s[42:43], s[44:45]
	s_cbranch_execz .LBB0_336
	v_ashrrev_i32_e32 v17, 31, v16
	v_readlane_b32 s8, v253, 6
	v_add_f32_e32 v10, v8, v9
	v_lshlrev_b64 v[8:9], 6, v[16:17]
	v_readlane_b32 s9, v253, 7
	s_nop 1
	v_lshl_add_u64 v[8:9], s[8:9], 0, v[8:9]
	v_lshl_add_u64 v[8:9], s[46:47], 2, v[8:9]
	s_lshl_b32 s46, s16, 2
	v_lshl_add_u64 v[8:9], v[8:9], 0, s[46:47]
	global_store_dword v[8:9], v10, off offset:-64
